# LRU gate GEMM section re-emitted: 12-deep Wg fragment ring read two groups ahead, k=0 MFMAs straight into the final accumulators, dependent MFMA pairs separated (was 8 serial read->wait->MFMA->nop rou
# speedup vs baseline: 1.0104x; 1.0033x over previous
; DEVI unsigned pk2(float lo, float hi) { f32x2 v = {lo, hi}; bf16x2_t b = __builtin_convertvector(v, bf16x2_t); return __builtin_bit_cast(unsigned, b); }
; DEVI float bflo(unsigned u) { return __uint_as_float(u << 16); }
; DEVI float bfhi(unsigned u) { return __uint_as_float(u & 0xffff0000u); }
; template <bool PASS_C>
; DEVI void lru_item(const P& p, int item, int next_item, uint4& u0, uint4& u1, uint4& u2, float& cpre, char* smem) {
;     ...
;     {
;         const int tok = tid >> 2, cg0 = (tid & 3) * 16;
;         uint4 r[4][2];
; #pragma unroll
;         for (int k = 0; k < 4; ++k) { r[k][0] = *(const uint4*)(us + (tok + k) * 64 + cg0); r[k][1] = *(const uint4*)(us + (tok + k) * 64 + cg0 + 8); }
;         float val[16];
; #pragma unroll
;         for (int e = 0; e < 16; ++e) {
;             const int ch = cg0 + e;
;             float a = prm[4 * 64 + ch];
; #pragma unroll
;             for (int k = 0; k < 4; ++k) {
;                 const uint4 q = r[k][e >> 3];
;                 const unsigned wd = ((e >> 1) & 3) == 0 ? q.x : (((e >> 1) & 3) == 1 ? q.y : (((e >> 1) & 3) == 2 ? q.z : q.w));
;                 a += prm[k * 64 + ch] * ((e & 1) ? bfhi(wd) : bflo(wd));
;             }
;             val[e] = a;
;         }
;         uint4 o;
;         o.x = pk2(val[0], val[1]); o.y = pk2(val[2], val[3]); o.z = pk2(val[4], val[5]); o.w = pk2(val[6], val[7]);
;         *(uint4*)(ucb + tok * 128 + ((((cg0 >> 3) + 0) ^ (tok & 7)) << 4)) = o;
;         o.x = pk2(val[8], val[9]); o.y = pk2(val[10], val[11]); o.z = pk2(val[12], val[13]); o.w = pk2(val[14], val[15]);
;         *(uint4*)(ucb + tok * 128 + ((((cg0 >> 3) + 1) ^ (tok & 7)) << 4)) = o;
;     }
.LBB0_510:
	s_waitcnt lgkmcnt(0)
	s_barrier
	ds_read_b128 v[32:35], v118 offset:35840
	ds_read_b128 v[12:15], v118 offset:35856
	ds_read_b128 v[36:39], v118 offset:35968
	ds_read_b128 v[16:19], v118 offset:35984
	ds_read_b128 v[40:43], v118 offset:36096
	ds_read_b128 v[20:23], v118 offset:36112
	ds_read_b128 v[44:47], v118 offset:36224
	ds_read_b128 v[24:27], v118 offset:36240
	ds_read_b128 v[48:51], v111 offset:33792
	ds_read_b128 v[52:55], v111 offset:32768
	ds_read_b128 v[56:59], v111 offset:32784
	ds_read_b128 v[60:63], v111 offset:32800
	ds_read_b128 v[28:31], v111 offset:32816
	ds_read_b128 v[64:67], v111 offset:33024
	ds_read_b128 v[92:95], v111 offset:33808
	s_waitcnt lgkmcnt(14)
	v_lshlrev_b32_e32 v96, 16, v32
	v_and_b32_e32 v97, 0xffff0000, v32
	s_waitcnt lgkmcnt(5)
	v_pk_fma_f32 v[48:49], v[52:53], v[96:97], v[48:49]
	ds_read_b128 v[96:99], v111 offset:33280
	ds_read_b128 v[146:149], v111 offset:33536
	ds_read_b128 v[150:153], v111 offset:33040
	v_lshlrev_b32_e32 v32, 16, v33
	v_and_b32_e32 v33, 0xffff0000, v33
	v_lshlrev_b32_e32 v154, 16, v36
	v_and_b32_e32 v155, 0xffff0000, v36
	v_lshlrev_b32_e32 v36, 16, v37
	v_and_b32_e32 v37, 0xffff0000, v37
	v_pk_fma_f32 v[32:33], v[54:55], v[32:33], v[50:51]
	v_lshlrev_b32_e32 v158, 16, v40
	v_and_b32_e32 v159, 0xffff0000, v40
	s_waitcnt lgkmcnt(4)
	v_pk_fma_f32 v[48:49], v[64:65], v[154:155], v[48:49]
	ds_read_b128 v[154:157], v111 offset:33296
	v_lshlrev_b32_e32 v40, 16, v41
	v_and_b32_e32 v41, 0xffff0000, v41
	v_pk_fma_f32 v[32:33], v[66:67], v[36:37], v[32:33]
	v_lshlrev_b32_e32 v162, 16, v44
	v_and_b32_e32 v163, 0xffff0000, v44
	s_waitcnt lgkmcnt(3)
	v_pk_fma_f32 v[48:49], v[96:97], v[158:159], v[48:49]
	ds_read_b128 v[158:161], v111 offset:33552
	v_lshlrev_b32_e32 v44, 16, v45
	v_and_b32_e32 v45, 0xffff0000, v45
	v_pk_fma_f32 v[32:33], v[98:99], v[40:41], v[32:33]
	v_lshlrev_b32_e32 v36, 16, v38
	s_waitcnt lgkmcnt(3)
	v_pk_fma_f32 v[98:99], v[148:149], v[44:45], v[32:33]
	v_lshlrev_b32_e32 v32, 16, v34
	v_and_b32_e32 v33, 0xffff0000, v34
	v_and_b32_e32 v37, 0xffff0000, v38
	v_pk_fma_f32 v[32:33], v[56:57], v[32:33], v[92:93]
	v_lshlrev_b32_e32 v40, 16, v42
	v_and_b32_e32 v41, 0xffff0000, v42
	s_waitcnt lgkmcnt(2)
	v_pk_fma_f32 v[32:33], v[150:151], v[36:37], v[32:33]
	v_lshlrev_b32_e32 v44, 16, v46
	v_and_b32_e32 v45, 0xffff0000, v46
	s_waitcnt lgkmcnt(1)
	v_pk_fma_f32 v[32:33], v[154:155], v[40:41], v[32:33]
	v_lshlrev_b32_e32 v34, 16, v39
	s_waitcnt lgkmcnt(0)
	v_pk_fma_f32 v[92:93], v[158:159], v[44:45], v[32:33]
	v_lshlrev_b32_e32 v32, 16, v35
	v_and_b32_e32 v33, 0xffff0000, v35
	v_and_b32_e32 v35, 0xffff0000, v39
	v_pk_fma_f32 v[32:33], v[58:59], v[32:33], v[94:95]
	v_lshlrev_b32_e32 v36, 16, v43
	v_and_b32_e32 v37, 0xffff0000, v43
	v_pk_fma_f32 v[32:33], v[152:153], v[34:35], v[32:33]
	v_lshlrev_b32_e32 v38, 16, v47
	v_and_b32_e32 v39, 0xffff0000, v47
	v_pk_fma_f32 v[32:33], v[156:157], v[36:37], v[32:33]
	v_lshlrev_b32_e32 v44, 16, v12
	v_pk_fma_f32 v[94:95], v[160:161], v[38:39], v[32:33]
	ds_read_b128 v[32:35], v111 offset:33824
	ds_read_b128 v[36:39], v111 offset:33056
	ds_read_b128 v[40:43], v111 offset:33840
	v_and_b32_e32 v45, 0xffff0000, v12
	v_pk_fma_f32 v[96:97], v[146:147], v[162:163], v[48:49]
	v_lshlrev_b32_e32 v12, 16, v13
	s_waitcnt lgkmcnt(2)
	v_pk_fma_f32 v[32:33], v[60:61], v[44:45], v[32:33]
	ds_read_b128 v[44:47], v111 offset:33312
	ds_read_b128 v[48:51], v111 offset:33568
	ds_read_b128 v[52:55], v111 offset:33072
	v_and_b32_e32 v13, 0xffff0000, v13
	v_lshlrev_b32_e32 v56, 16, v16
	v_and_b32_e32 v57, 0xffff0000, v16
	v_lshlrev_b32_e32 v16, 16, v17
	v_and_b32_e32 v17, 0xffff0000, v17
	v_pk_fma_f32 v[12:13], v[62:63], v[12:13], v[34:35]
	v_lshlrev_b32_e32 v64, 16, v20
	v_and_b32_e32 v65, 0xffff0000, v20
	s_waitcnt lgkmcnt(4)
	v_pk_fma_f32 v[32:33], v[36:37], v[56:57], v[32:33]
	ds_read_b128 v[56:59], v111 offset:33328
	v_lshlrev_b32_e32 v20, 16, v21
	v_and_b32_e32 v21, 0xffff0000, v21
	v_pk_fma_f32 v[12:13], v[38:39], v[16:17], v[12:13]
	v_lshlrev_b32_e32 v146, 16, v24
	v_and_b32_e32 v147, 0xffff0000, v24
	s_waitcnt lgkmcnt(3)
	v_pk_fma_f32 v[32:33], v[44:45], v[64:65], v[32:33]
	ds_read_b128 v[64:67], v111 offset:33584
	v_lshlrev_b32_e32 v24, 16, v25
	v_and_b32_e32 v25, 0xffff0000, v25
	v_pk_fma_f32 v[12:13], v[46:47], v[20:21], v[12:13]
	v_lshlrev_b32_e32 v20, 16, v18
	s_waitcnt lgkmcnt(3)
	v_pk_fma_f32 v[16:17], v[50:51], v[24:25], v[12:13]
	v_lshlrev_b32_e32 v12, 16, v14
	v_and_b32_e32 v13, 0xffff0000, v14
	v_and_b32_e32 v21, 0xffff0000, v18
	v_pk_fma_f32 v[12:13], v[28:29], v[12:13], v[40:41]
	v_lshlrev_b32_e32 v24, 16, v22
	v_and_b32_e32 v25, 0xffff0000, v22
	s_waitcnt lgkmcnt(2)
	v_pk_fma_f32 v[12:13], v[52:53], v[20:21], v[12:13]
	v_lshlrev_b32_e32 v34, 16, v26
	v_and_b32_e32 v35, 0xffff0000, v26
	s_waitcnt lgkmcnt(1)
	v_pk_fma_f32 v[12:13], v[56:57], v[24:25], v[12:13]
	v_lshlrev_b32_e32 v14, 16, v19
	s_waitcnt lgkmcnt(0)
	v_pk_fma_f32 v[20:21], v[64:65], v[34:35], v[12:13]
	v_lshlrev_b32_e32 v12, 16, v15
	v_and_b32_e32 v13, 0xffff0000, v15
	v_and_b32_e32 v15, 0xffff0000, v19
	v_pk_fma_f32 v[12:13], v[30:31], v[12:13], v[42:43]
	v_lshlrev_b32_e32 v18, 16, v23
	v_and_b32_e32 v19, 0xffff0000, v23
	v_pk_fma_f32 v[12:13], v[54:55], v[14:15], v[12:13]
	v_lshlrev_b32_e32 v22, 16, v27
	v_and_b32_e32 v23, 0xffff0000, v27
	v_pk_fma_f32 v[12:13], v[58:59], v[18:19], v[12:13]
	v_pk_fma_f32 v[32:33], v[48:49], v[146:147], v[32:33]
	v_pk_fma_f32 v[18:19], v[66:67], v[22:23], v[12:13]
	v_cvt_pk_bf16_f32 v12, v96, v97
	v_cvt_pk_bf16_f32 v13, v98, v99
	v_cvt_pk_bf16_f32 v14, v92, v93
	v_cvt_pk_bf16_f32 v15, v94, v95
	ds_write_b128 v119, v[12:15] offset:44544
	v_cvt_pk_bf16_f32 v12, v32, v33
	v_cvt_pk_bf16_f32 v13, v16, v17
	v_cvt_pk_bf16_f32 v14, v20, v21
	v_cvt_pk_bf16_f32 v15, v18, v19
	ds_write_b128 v120, v[12:15] offset:44544
	v_add_u32_e32 v12, v113, v114
	s_waitcnt lgkmcnt(0)
	s_barrier
; template <bool PASS_C>
; DEVI void lru_item(const P& p, int item, int next_item, uint4& u0, uint4& u1, uint4& u2, float& cpre, char* smem) {
;     ...
;     {
;         bf16x8 af[2];
; #pragma unroll
;         for (int kk = 0; kk < 2; ++kk) af[kk] = *(const bf16x8*)(ucb + (16 * w + fr) * 128 + (((kk * 4 + fq) ^ (fr & 7)) << 4));
; #pragma unroll
;         for (int n = 0; n < 16; ++n)
; #pragma unroll
;             for (int kk = 0; kk < 2; ++kk) {
;                 const bf16x8 bfr = *(const bf16x8*)(smem + (16 * n + fr) * 128 + (((kk * 4 + fq) ^ (fr & 7)) << 4));
;                 acc[n] = __builtin_amdgcn_mfma_f32_16x16x32_bf16(af[kk], bfr, acc[n], 0, 0, 0);
;             }
;     }
;     ...
;         for (int d = 0; d < 2; ++d) {
;             const float ba = prm[(5 + d) * 64 + ch], bx = prm[(7 + d) * 64 + ch], nsp8 = prm[(9 + d) * 64 + ch];
; #pragma unroll
;             for (int j = 0; j < 4; ++j) {
;                 const float r = __builtin_amdgcn_rcpf(1.0f + __builtin_amdgcn_exp2f(__builtin_fmaf(acc[(2 * d) * 4 + nn][j], -LOG2E, ba)));
;                 const float ig = __builtin_amdgcn_rcpf(1.0f + __builtin_amdgcn_exp2f(__builtin_fmaf(acc[(2 * d + 1) * 4 + nn][j], -LOG2E, bx)));
;                 const float a_ = __builtin_amdgcn_exp2f(nsp8 * r);
;                 av[nn][d][j] = a_;
;                 bv[nn][d][j] = __builtin_amdgcn_sqrtf(__builtin_fmaf(-a_, a_, 1.0f)) * ig * uc[j];
	v_add_u32_e32 v75, v112, v114
	v_add_u32_e32 v20, v113, v115
	v_add_u32_e32 v77, v112, v115
	ds_read_b128 v[12:15], v12 offset:44544
	ds_read_b128 v[92:95], v20 offset:44544
	ds_read_b32 v83, v116 offset:35072
	ds_read_b128 v[232:235], v75
	ds_read_b128 v[236:239], v77
	ds_read_b128 v[240:243], v75 offset:2048
	ds_read_b128 v[244:247], v77 offset:2048
	ds_read_b128 v[248:251], v75 offset:4096
	ds_read_b128 v[158:161], v77 offset:4096
	ds_read_b128 v[252:255], v75 offset:6144
	ds_read_b128 v[218:221], v77 offset:6144
	s_waitcnt lgkmcnt(4)
	v_mfma_f32_16x16x32_bf16 v[146:149], v[12:15], v[232:235], 0
	ds_read_b128 v[222:225], v75 offset:8192
	ds_read_b128 v[226:229], v77 offset:8192
	ds_read_b128 v[96:99], v75 offset:10240
	ds_read_b128 v[154:157], v77 offset:10240
	v_mfma_f32_16x16x32_bf16 v[56:59], v[12:15], v[240:243], 0
	v_mfma_f32_16x16x32_bf16 v[146:149], v[92:95], v[236:239], v[146:149]
	v_mfma_f32_16x16x32_bf16 v[56:59], v[92:95], v[244:247], v[56:59]
	s_waitcnt lgkmcnt(4)
	v_mfma_f32_16x16x32_bf16 v[40:43], v[12:15], v[248:251], 0
	ds_read_b128 v[232:235], v75 offset:12288
	ds_read_b128 v[236:239], v77 offset:12288
	ds_read_b128 v[240:243], v75 offset:14336
	ds_read_b128 v[244:247], v77 offset:14336
	v_mfma_f32_16x16x32_bf16 v[24:27], v[12:15], v[252:255], 0
	v_mfma_f32_16x16x32_bf16 v[40:43], v[92:95], v[158:161], v[40:43]
	v_mfma_f32_16x16x32_bf16 v[24:27], v[92:95], v[218:221], v[24:27]
	s_waitcnt lgkmcnt(4)
	v_mfma_f32_16x16x32_bf16 v[150:153], v[12:15], v[222:225], 0
	ds_read_b128 v[248:251], v75 offset:16384
	ds_read_b128 v[158:161], v77 offset:16384
	ds_read_b128 v[252:255], v75 offset:18432
	ds_read_b128 v[218:221], v77 offset:18432
	v_mfma_f32_16x16x32_bf16 v[52:55], v[12:15], v[96:99], 0
	v_mfma_f32_16x16x32_bf16 v[150:153], v[92:95], v[226:229], v[150:153]
	v_mfma_f32_16x16x32_bf16 v[52:55], v[92:95], v[154:157], v[52:55]
	s_waitcnt lgkmcnt(4)
	v_mfma_f32_16x16x32_bf16 v[36:39], v[12:15], v[232:235], 0
	ds_read_b128 v[222:225], v75 offset:20480
	ds_read_b128 v[226:229], v77 offset:20480
	ds_read_b128 v[96:99], v75 offset:22528
	ds_read_b128 v[154:157], v77 offset:22528
	v_mfma_f32_16x16x32_bf16 v[20:23], v[12:15], v[240:243], 0
	v_mfma_f32_16x16x32_bf16 v[36:39], v[92:95], v[236:239], v[36:39]
	v_mfma_f32_16x16x32_bf16 v[20:23], v[92:95], v[244:247], v[20:23]
	s_waitcnt lgkmcnt(4)
	v_mfma_f32_16x16x32_bf16 v[64:67], v[12:15], v[248:251], 0
	ds_read_b128 v[232:235], v75 offset:24576
	ds_read_b128 v[236:239], v77 offset:24576
	ds_read_b128 v[240:243], v75 offset:26624
	ds_read_b128 v[244:247], v77 offset:26624
	v_mfma_f32_16x16x32_bf16 v[48:51], v[12:15], v[252:255], 0
	v_mfma_f32_16x16x32_bf16 v[64:67], v[92:95], v[158:161], v[64:67]
	v_mfma_f32_16x16x32_bf16 v[48:51], v[92:95], v[218:221], v[48:51]
	s_waitcnt lgkmcnt(4)
	v_mfma_f32_16x16x32_bf16 v[32:35], v[12:15], v[222:225], 0
	ds_read_b128 v[248:251], v75 offset:28672
	ds_read_b128 v[252:255], v75 offset:30720
	ds_read_b128 v[158:161], v77 offset:28672
	v_mfma_f32_16x16x32_bf16 v[16:19], v[12:15], v[96:99], 0
	v_mfma_f32_16x16x32_bf16 v[32:35], v[92:95], v[226:229], v[32:35]
	v_mfma_f32_16x16x32_bf16 v[16:19], v[92:95], v[154:157], v[16:19]
	s_waitcnt lgkmcnt(3)
	v_mfma_f32_16x16x32_bf16 v[60:63], v[12:15], v[232:235], 0
	v_mfma_f32_16x16x32_bf16 v[44:47], v[12:15], v[240:243], 0
	v_mfma_f32_16x16x32_bf16 v[60:63], v[92:95], v[236:239], v[60:63]
	v_mfma_f32_16x16x32_bf16 v[44:47], v[92:95], v[244:247], v[44:47]
	s_waitcnt lgkmcnt(1)
	v_mfma_f32_16x16x32_bf16 v[28:31], v[12:15], v[248:251], 0
	v_mfma_f32_16x16x32_bf16 v[12:15], v[12:15], v[252:255], 0
	ds_read_b128 v[96:99], v77 offset:30720
	ds_read2st64_b32 v[154:155], v116 offset0:133 offset1:135
	ds_read_u16 v75, v121 offset:44544
	ds_read_u16 v77, v122 offset:44544
	ds_read_u16 v79, v123 offset:44544
	ds_read_u16 v85, v124 offset:44544
	s_waitcnt lgkmcnt(4)
	v_fmamk_f32 v81, v146, 0xbfb8aa3b, v154
	v_exp_f32_e32 v81, v81
	v_fmamk_f32 v91, v149, 0xbfb8aa3b, v154
	v_exp_f32_e32 v91, v91
	v_mfma_f32_16x16x32_bf16 v[28:31], v[92:95], v[158:161], v[28:31]
	v_add_f32_e32 v81, 1.0, v81
	v_rcp_f32_e32 v87, v81
	v_fmamk_f32 v81, v147, 0xbfb8aa3b, v154
	v_exp_f32_e32 v89, v81
	s_waitcnt lgkmcnt(0)
	v_lshlrev_b32_e32 v81, 16, v85
	v_mul_f32_e32 v85, v83, v87
	v_mfma_f32_16x16x32_bf16 v[12:15], v[92:95], v[96:99], v[12:15]
	v_add_f32_e32 v87, 1.0, v89
	v_fmamk_f32 v89, v148, 0xbfb8aa3b, v154
	v_exp_f32_e32 v89, v89
	v_add_f32_e32 v91, 1.0, v91
	v_fmamk_f32 v93, v150, 0xbfb8aa3b, v155
	v_rcp_f32_e32 v87, v87
	v_add_f32_e32 v89, 1.0, v89
	v_exp_f32_e32 v85, v85
	v_rcp_f32_e32 v89, v89
	v_rcp_f32_e32 v91, v91
	v_exp_f32_e32 v93, v93
	v_mul_f32_e32 v87, v83, v87
	v_mul_f32_e32 v89, v83, v89
	v_mul_f32_e32 v83, v83, v91
	v_add_f32_e32 v91, 1.0, v93
	v_fma_f32 v93, -v85, v85, 1.0
	v_rcp_f32_e32 v91, v91
	v_sqrt_f32_e32 v93, v93
	v_fmamk_f32 v94, v151, 0xbfb8aa3b, v155
	v_exp_f32_e32 v87, v87
	v_exp_f32_e32 v94, v94
	v_lshlrev_b32_e32 v75, 16, v75
	v_mul_f32_e32 v91, v91, v93
	v_mul_f32_e32 v91, v91, v75
	v_mul_f32_e32 v92, v85, v87
	v_fmac_f32_e32 v91, 0, v85
	v_add_f32_e32 v85, 1.0, v94
	v_fma_f32 v93, -v87, v87, 1.0
	v_rcp_f32_e32 v85, v85
	v_sqrt_f32_e32 v93, v93
	v_mul_f32_e32 v87, v87, v91
	v_fmamk_f32 v91, v152, 0xbfb8aa3b, v155
	v_exp_f32_e32 v89, v89
	v_exp_f32_e32 v91, v91
	v_lshlrev_b32_e32 v77, 16, v77
	v_mul_f32_e32 v85, v85, v93
	v_fmac_f32_e32 v87, v85, v77
	v_fmac_f32_e32 v155, 0xbfb8aa3b, v153
	v_exp_f32_e32 v83, v83
	v_mul_f32_e32 v85, v89, v87
	v_add_f32_e32 v87, 1.0, v91
	v_exp_f32_e32 v91, v155
	v_mul_f32_e32 v92, v89, v92
	v_fma_f32 v89, -v89, v89, 1.0
	v_rcp_f32_e32 v87, v87
	v_sqrt_f32_e32 v89, v89
	v_add_f32_e32 v91, 1.0, v91
	v_fma_f32 v93, -v83, v83, 1.0
	v_rcp_f32_e32 v91, v91
	v_sqrt_f32_e32 v93, v93
	v_lshlrev_b32_e32 v79, 16, v79
	v_mul_f32_e32 v87, v87, v89
	v_fmac_f32_e32 v85, v87, v79
	v_mul_f32_e32 v92, v83, v92
	v_mul_f32_e32 v83, v83, v85
	v_mul_f32_e32 v85, v91, v93
	v_fmac_f32_e32 v83, v85, v81
	v_mov_b32_e32 v96, v92
	v_mov_b32_e32 v85, v83
	s_nop 0
	v_permlane16_swap_b32_e32 v92, v96
	v_permlane16_swap_b32_e32 v83, v85
	v_mov_b32_e32 v94, v92
	v_mov_b32_e32 v95, v96
	v_mov_b32_e32 v97, v83
	v_mov_b32_e32 v99, v85
	v_permlane32_swap_b32_e32 v92, v94
	v_permlane32_swap_b32_e32 v96, v95
	v_permlane32_swap_b32_e32 v83, v97
	v_permlane32_swap_b32_e32 v85, v99
	s_and_saveexec_b64 s[12:13], s[8:9]
	s_cbranch_execz .LBB0_512
	v_fmac_f32_e32 v83, 0, v92
	v_fmac_f32_e32 v85, v83, v96
	v_mul_f32_e32 v93, v85, v94
	v_pk_mul_f32 v[146:147], v[92:93], v[96:97]
	v_pk_add_f32 v[92:93], v[92:93], v[96:97]
	v_mov_b32_e32 v96, v95
	v_mov_b32_e32 v92, v146
	v_mov_b32_e32 v98, v95
	v_pk_mul_f32 v[146:147], v[146:147], v[94:95]
	v_pk_fma_f32 v[92:93], v[92:93], v[94:95], v[98:99]
	v_pk_mul_f32 v[96:97], v[146:147], v[96:97]
	s_nop 0
	v_mov_b32_e32 v97, v93
	ds_write_b64 v141, v[96:97] offset:52736

; DEVI unsigned pk2(float lo, float hi) { f32x2 v = {lo, hi}; bf16x2_t b = __builtin_convertvector(v, bf16x2_t); return __builtin_bit_cast(unsigned, b); }
; DEVI float bflo(unsigned u) { return __uint_as_float(u << 16); }
; DEVI float bfhi(unsigned u) { return __uint_as_float(u & 0xffff0000u); }
; template <bool PASS_C>
; DEVI void lru_item(const P& p, int item, int next_item, uint4& u0, uint4& u1, uint4& u2, float& cpre, char* smem) {
;     ...
;     {
;         const int tok = tid >> 2, cg0 = (tid & 3) * 16;
;         uint4 r[4][2];
; #pragma unroll
;         for (int k = 0; k < 4; ++k) { r[k][0] = *(const uint4*)(us + (tok + k) * 64 + cg0); r[k][1] = *(const uint4*)(us + (tok + k) * 64 + cg0 + 8); }
;         float val[16];
; #pragma unroll
;         for (int e = 0; e < 16; ++e) {
;             const int ch = cg0 + e;
;             float a = prm[4 * 64 + ch];
; #pragma unroll
;             for (int k = 0; k < 4; ++k) {
;                 const uint4 q = r[k][e >> 3];
;                 const unsigned wd = ((e >> 1) & 3) == 0 ? q.x : (((e >> 1) & 3) == 1 ? q.y : (((e >> 1) & 3) == 2 ? q.z : q.w));
;                 a += prm[k * 64 + ch] * ((e & 1) ? bfhi(wd) : bflo(wd));
;             }
;             val[e] = a;
;         }
;         uint4 o;
;         o.x = pk2(val[0], val[1]); o.y = pk2(val[2], val[3]); o.z = pk2(val[4], val[5]); o.w = pk2(val[6], val[7]);
;         *(uint4*)(ucb + tok * 128 + ((((cg0 >> 3) + 0) ^ (tok & 7)) << 4)) = o;
;         o.x = pk2(val[8], val[9]); o.y = pk2(val[10], val[11]); o.z = pk2(val[12], val[13]); o.w = pk2(val[14], val[15]);
;         *(uint4*)(ucb + tok * 128 + ((((cg0 >> 3) + 1) ^ (tok & 7)) << 4)) = o;
;     }
.LBB0_739:
	v_lshlrev_b64 v[106:107], 10, v[22:23]
	s_waitcnt lgkmcnt(0)
	s_barrier
	ds_read_b128 v[42:45], v127 offset:35840
	ds_read_b128 v[22:25], v127 offset:35856
	ds_read_b128 v[46:49], v127 offset:35968
	ds_read_b128 v[26:29], v127 offset:35984
	ds_read_b128 v[50:53], v127 offset:36096
	ds_read_b128 v[30:33], v127 offset:36112
	ds_read_b128 v[54:57], v127 offset:36224
	ds_read_b128 v[34:37], v127 offset:36240
	ds_read_b128 v[58:61], v117 offset:33792
	ds_read_b128 v[62:65], v117 offset:32768
	ds_read_b128 v[66:69], v117 offset:32784
	ds_read_b128 v[70:73], v117 offset:32800
	ds_read_b128 v[38:41], v117 offset:32816
	ds_read_b128 v[74:77], v117 offset:33024
	ds_read_b128 v[158:161], v117 offset:33808
	s_waitcnt lgkmcnt(14)
	v_lshlrev_b32_e32 v162, 16, v42
	v_and_b32_e32 v163, 0xffff0000, v42
	s_waitcnt lgkmcnt(5)
	v_pk_fma_f32 v[58:59], v[62:63], v[162:163], v[58:59]
	ds_read_b128 v[162:165], v117 offset:33280
	ds_read_b128 v[166:169], v117 offset:33536
	ds_read_b128 v[184:187], v117 offset:33040
	v_lshlrev_b32_e32 v42, 16, v43
	v_and_b32_e32 v43, 0xffff0000, v43
	v_lshlrev_b32_e32 v170, 16, v46
	v_and_b32_e32 v171, 0xffff0000, v46
	v_lshlrev_b32_e32 v46, 16, v47
	v_and_b32_e32 v47, 0xffff0000, v47
	v_pk_fma_f32 v[42:43], v[64:65], v[42:43], v[60:61]
	v_lshlrev_b32_e32 v192, 16, v50
	v_and_b32_e32 v193, 0xffff0000, v50
	s_waitcnt lgkmcnt(4)
	v_pk_fma_f32 v[58:59], v[74:75], v[170:171], v[58:59]
	ds_read_b128 v[188:191], v117 offset:33296
	v_lshlrev_b32_e32 v50, 16, v51
	v_and_b32_e32 v51, 0xffff0000, v51
	v_pk_fma_f32 v[42:43], v[76:77], v[46:47], v[42:43]
	v_lshlrev_b32_e32 v196, 16, v54
	v_and_b32_e32 v197, 0xffff0000, v54
	s_waitcnt lgkmcnt(3)
	v_pk_fma_f32 v[58:59], v[162:163], v[192:193], v[58:59]
	ds_read_b128 v[192:195], v117 offset:33552
	v_lshlrev_b32_e32 v54, 16, v55
	v_and_b32_e32 v55, 0xffff0000, v55
	v_pk_fma_f32 v[42:43], v[164:165], v[50:51], v[42:43]
	v_lshlrev_b32_e32 v46, 16, v48
	s_waitcnt lgkmcnt(3)
	v_pk_fma_f32 v[164:165], v[168:169], v[54:55], v[42:43]
	v_lshlrev_b32_e32 v42, 16, v44
	v_and_b32_e32 v43, 0xffff0000, v44
	v_and_b32_e32 v47, 0xffff0000, v48
	v_pk_fma_f32 v[42:43], v[66:67], v[42:43], v[158:159]
	v_lshlrev_b32_e32 v50, 16, v52
	v_and_b32_e32 v51, 0xffff0000, v52
	s_waitcnt lgkmcnt(2)
	v_pk_fma_f32 v[42:43], v[184:185], v[46:47], v[42:43]
	v_lshlrev_b32_e32 v54, 16, v56
	v_and_b32_e32 v55, 0xffff0000, v56
	s_waitcnt lgkmcnt(1)
	v_pk_fma_f32 v[42:43], v[188:189], v[50:51], v[42:43]
	v_lshlrev_b32_e32 v44, 16, v49
	s_waitcnt lgkmcnt(0)
	v_pk_fma_f32 v[158:159], v[192:193], v[54:55], v[42:43]
	v_lshlrev_b32_e32 v42, 16, v45
	v_and_b32_e32 v43, 0xffff0000, v45
	v_and_b32_e32 v45, 0xffff0000, v49
	v_pk_fma_f32 v[42:43], v[68:69], v[42:43], v[160:161]
	v_lshlrev_b32_e32 v46, 16, v53
	v_and_b32_e32 v47, 0xffff0000, v53
	v_pk_fma_f32 v[42:43], v[186:187], v[44:45], v[42:43]
	v_lshlrev_b32_e32 v48, 16, v57
	v_and_b32_e32 v49, 0xffff0000, v57
	v_pk_fma_f32 v[42:43], v[190:191], v[46:47], v[42:43]
	v_lshlrev_b32_e32 v54, 16, v22
	v_pk_fma_f32 v[160:161], v[194:195], v[48:49], v[42:43]
	ds_read_b128 v[42:45], v117 offset:33824
	ds_read_b128 v[46:49], v117 offset:33056
	ds_read_b128 v[50:53], v117 offset:33840
	v_and_b32_e32 v55, 0xffff0000, v22
	v_pk_fma_f32 v[162:163], v[166:167], v[196:197], v[58:59]
	v_lshlrev_b32_e32 v22, 16, v23
	s_waitcnt lgkmcnt(2)
	v_pk_fma_f32 v[42:43], v[70:71], v[54:55], v[42:43]
	ds_read_b128 v[54:57], v117 offset:33312
	ds_read_b128 v[58:61], v117 offset:33568
	ds_read_b128 v[62:65], v117 offset:33072
	v_and_b32_e32 v23, 0xffff0000, v23
	v_lshlrev_b32_e32 v66, 16, v26
	v_and_b32_e32 v67, 0xffff0000, v26
	v_lshlrev_b32_e32 v26, 16, v27
	v_and_b32_e32 v27, 0xffff0000, v27
	v_pk_fma_f32 v[22:23], v[72:73], v[22:23], v[44:45]
	v_lshlrev_b32_e32 v74, 16, v30
	v_and_b32_e32 v75, 0xffff0000, v30
	s_waitcnt lgkmcnt(4)
	v_pk_fma_f32 v[42:43], v[46:47], v[66:67], v[42:43]
	ds_read_b128 v[66:69], v117 offset:33328
	v_lshlrev_b32_e32 v30, 16, v31
	v_and_b32_e32 v31, 0xffff0000, v31
	v_pk_fma_f32 v[22:23], v[48:49], v[26:27], v[22:23]
	v_lshlrev_b32_e32 v166, 16, v34
	v_and_b32_e32 v167, 0xffff0000, v34
	s_waitcnt lgkmcnt(3)
	v_pk_fma_f32 v[42:43], v[54:55], v[74:75], v[42:43]
	ds_read_b128 v[74:77], v117 offset:33584
	v_lshlrev_b32_e32 v34, 16, v35
	v_and_b32_e32 v35, 0xffff0000, v35
	v_pk_fma_f32 v[22:23], v[56:57], v[30:31], v[22:23]
	v_lshlrev_b32_e32 v30, 16, v28
	s_waitcnt lgkmcnt(3)
	v_pk_fma_f32 v[26:27], v[60:61], v[34:35], v[22:23]
	v_lshlrev_b32_e32 v22, 16, v24
	v_and_b32_e32 v23, 0xffff0000, v24
	v_and_b32_e32 v31, 0xffff0000, v28
	v_pk_fma_f32 v[22:23], v[38:39], v[22:23], v[50:51]
	v_lshlrev_b32_e32 v34, 16, v32
	v_and_b32_e32 v35, 0xffff0000, v32
	s_waitcnt lgkmcnt(2)
	v_pk_fma_f32 v[22:23], v[62:63], v[30:31], v[22:23]
	v_lshlrev_b32_e32 v44, 16, v36
	v_and_b32_e32 v45, 0xffff0000, v36
	s_waitcnt lgkmcnt(1)
	v_pk_fma_f32 v[22:23], v[66:67], v[34:35], v[22:23]
	v_lshlrev_b32_e32 v24, 16, v29
	s_waitcnt lgkmcnt(0)
	v_pk_fma_f32 v[30:31], v[74:75], v[44:45], v[22:23]
	v_lshlrev_b32_e32 v22, 16, v25
	v_and_b32_e32 v23, 0xffff0000, v25
	v_and_b32_e32 v25, 0xffff0000, v29
	v_pk_fma_f32 v[22:23], v[40:41], v[22:23], v[52:53]
	v_lshlrev_b32_e32 v28, 16, v33
	v_and_b32_e32 v29, 0xffff0000, v33
	v_pk_fma_f32 v[22:23], v[64:65], v[24:25], v[22:23]
	v_lshlrev_b32_e32 v32, 16, v37
	v_and_b32_e32 v33, 0xffff0000, v37
	v_pk_fma_f32 v[22:23], v[68:69], v[28:29], v[22:23]
	v_pk_fma_f32 v[42:43], v[58:59], v[166:167], v[42:43]
	v_pk_fma_f32 v[28:29], v[76:77], v[32:33], v[22:23]
	v_cvt_pk_bf16_f32 v22, v162, v163
	v_cvt_pk_bf16_f32 v23, v164, v165
	v_cvt_pk_bf16_f32 v24, v158, v159
	v_cvt_pk_bf16_f32 v25, v160, v161
	ds_write_b128 v128, v[22:25] offset:44544
	v_cvt_pk_bf16_f32 v22, v42, v43
	v_cvt_pk_bf16_f32 v23, v26, v27
	v_cvt_pk_bf16_f32 v24, v30, v31
	v_cvt_pk_bf16_f32 v25, v28, v29
	ds_write_b128 v129, v[22:25] offset:44544
	v_add_u32_e32 v22, v119, v120
	s_waitcnt lgkmcnt(0)
	s_barrier
; template <bool PASS_C>
; DEVI void lru_item(const P& p, int item, int next_item, uint4& u0, uint4& u1, uint4& u2, float& cpre, char* smem) {
;     ...
;     {
;         bf16x8 af[2];
; #pragma unroll
;         for (int kk = 0; kk < 2; ++kk) af[kk] = *(const bf16x8*)(ucb + (16 * w + fr) * 128 + (((kk * 4 + fq) ^ (fr & 7)) << 4));
; #pragma unroll
;         for (int n = 0; n < 16; ++n)
; #pragma unroll
;             for (int kk = 0; kk < 2; ++kk) {
;                 const bf16x8 bfr = *(const bf16x8*)(smem + (16 * n + fr) * 128 + (((kk * 4 + fq) ^ (fr & 7)) << 4));
;                 acc[n] = __builtin_amdgcn_mfma_f32_16x16x32_bf16(af[kk], bfr, acc[n], 0, 0, 0);
;             }
;     }
	v_add_u32_e32 v87, v118, v120
	v_add_u32_e32 v30, v119, v121
	v_add_u32_e32 v89, v118, v121
	ds_read_b128 v[26:29], v22 offset:44544
	ds_read_b128 v[158:161], v30 offset:44544
	ds_read_b32 v93, v122 offset:35072
	ds_read_b128 v[232:235], v87
	ds_read_b128 v[236:239], v89
	ds_read_b128 v[240:243], v87 offset:2048
	ds_read_b128 v[244:247], v89 offset:2048
	ds_read_b128 v[248:251], v87 offset:4096
	ds_read_b128 v[192:195], v89 offset:4096
	ds_read_b128 v[252:255], v87 offset:6144
	ds_read_b128 v[218:221], v89 offset:6144
	s_waitcnt lgkmcnt(4)
	v_mfma_f32_16x16x32_bf16 v[166:169], v[26:29], v[232:235], 0
	ds_read_b128 v[222:225], v87 offset:8192
	ds_read_b128 v[226:229], v89 offset:8192
	ds_read_b128 v[162:165], v87 offset:10240
	ds_read_b128 v[188:191], v89 offset:10240
	v_mfma_f32_16x16x32_bf16 v[62:65], v[26:29], v[240:243], 0
	v_mfma_f32_16x16x32_bf16 v[166:169], v[158:161], v[236:239], v[166:169]
	v_mfma_f32_16x16x32_bf16 v[62:65], v[158:161], v[244:247], v[62:65]
	s_waitcnt lgkmcnt(4)
	v_mfma_f32_16x16x32_bf16 v[46:49], v[26:29], v[248:251], 0
	ds_read_b128 v[232:235], v87 offset:12288
	ds_read_b128 v[236:239], v89 offset:12288
	ds_read_b128 v[240:243], v87 offset:14336
	ds_read_b128 v[244:247], v89 offset:14336
	v_mfma_f32_16x16x32_bf16 v[30:33], v[26:29], v[252:255], 0
	v_mfma_f32_16x16x32_bf16 v[46:49], v[158:161], v[192:195], v[46:49]
	v_mfma_f32_16x16x32_bf16 v[30:33], v[158:161], v[218:221], v[30:33]
	s_waitcnt lgkmcnt(4)
	v_mfma_f32_16x16x32_bf16 v[184:187], v[26:29], v[222:225], 0
	ds_read_b128 v[248:251], v87 offset:16384
	ds_read_b128 v[192:195], v89 offset:16384
	ds_read_b128 v[252:255], v87 offset:18432
	ds_read_b128 v[218:221], v89 offset:18432
	v_mfma_f32_16x16x32_bf16 v[66:69], v[26:29], v[162:165], 0
	v_mfma_f32_16x16x32_bf16 v[184:187], v[158:161], v[226:229], v[184:187]
	v_mfma_f32_16x16x32_bf16 v[66:69], v[158:161], v[188:191], v[66:69]
	s_waitcnt lgkmcnt(4)
	v_mfma_f32_16x16x32_bf16 v[50:53], v[26:29], v[232:235], 0
	ds_read_b128 v[222:225], v87 offset:20480
	ds_read_b128 v[226:229], v89 offset:20480
	ds_read_b128 v[162:165], v87 offset:22528
	ds_read_b128 v[188:191], v89 offset:22528
	v_mfma_f32_16x16x32_bf16 v[34:37], v[26:29], v[240:243], 0
	v_mfma_f32_16x16x32_bf16 v[50:53], v[158:161], v[236:239], v[50:53]
	v_mfma_f32_16x16x32_bf16 v[34:37], v[158:161], v[244:247], v[34:37]
	s_waitcnt lgkmcnt(4)
	v_mfma_f32_16x16x32_bf16 v[70:73], v[26:29], v[248:251], 0
	ds_read_b128 v[232:235], v87 offset:24576
	ds_read_b128 v[236:239], v89 offset:24576
	ds_read_b128 v[240:243], v87 offset:26624
	ds_read_b128 v[244:247], v89 offset:26624
	v_mfma_f32_16x16x32_bf16 v[54:57], v[26:29], v[252:255], 0
	v_mfma_f32_16x16x32_bf16 v[70:73], v[158:161], v[192:195], v[70:73]
	v_mfma_f32_16x16x32_bf16 v[54:57], v[158:161], v[218:221], v[54:57]
	s_waitcnt lgkmcnt(4)
	v_mfma_f32_16x16x32_bf16 v[38:41], v[26:29], v[222:225], 0
	ds_read_b128 v[248:251], v87 offset:28672
	ds_read_b128 v[252:255], v87 offset:30720
	ds_read_b128 v[192:195], v89 offset:28672
	v_mfma_f32_16x16x32_bf16 v[22:25], v[26:29], v[162:165], 0
	v_mfma_f32_16x16x32_bf16 v[38:41], v[158:161], v[226:229], v[38:41]
	v_mfma_f32_16x16x32_bf16 v[22:25], v[158:161], v[188:191], v[22:25]
	s_waitcnt lgkmcnt(3)
	v_mfma_f32_16x16x32_bf16 v[74:77], v[26:29], v[232:235], 0
	v_mfma_f32_16x16x32_bf16 v[58:61], v[26:29], v[240:243], 0
	v_mfma_f32_16x16x32_bf16 v[74:77], v[158:161], v[236:239], v[74:77]
	v_mfma_f32_16x16x32_bf16 v[58:61], v[158:161], v[244:247], v[58:61]
	s_waitcnt lgkmcnt(1)
	v_mfma_f32_16x16x32_bf16 v[42:45], v[26:29], v[248:251], 0
	v_mfma_f32_16x16x32_bf16 v[26:29], v[26:29], v[252:255], 0
	ds_read2st64_b32 v[170:171], v122 offset0:133 offset1:135
	ds_read_b128 v[162:165], v89 offset:30720
	ds_read_u16 v87, v130 offset:44544
	ds_read_u16 v89, v131 offset:44544
	ds_read_u16 v91, v132 offset:44544
	s_waitcnt lgkmcnt(4)
	v_fmamk_f32 v95, v166, 0xbfb8aa3b, v170
	v_exp_f32_e32 v95, v95
	v_mfma_f32_16x16x32_bf16 v[42:45], v[158:161], v[192:195], v[42:45]
	v_fmamk_f32 v99, v168, 0xbfb8aa3b, v170
	v_fmamk_f32 v101, v186, 0xbfb8aa3b, v171
	v_exp_f32_e32 v99, v99
	s_waitcnt lgkmcnt(3)
	v_mfma_f32_16x16x32_bf16 v[26:29], v[158:161], v[162:165], v[26:29]
	s_waitcnt lgkmcnt(2)
	v_lshlrev_b32_e32 v164, 16, v87
	s_waitcnt lgkmcnt(1)
	v_lshlrev_b32_e32 v161, 16, v89
	v_add_f32_e32 v87, 1.0, v95
	v_fmamk_f32 v89, v184, 0xbfb8aa3b, v171
	v_exp_f32_e32 v89, v89
	v_rcp_f32_e32 v87, v87
	s_waitcnt lgkmcnt(0)
	v_lshlrev_b32_e32 v162, 16, v91
	ds_read_u16 v91, v133 offset:44544
	v_add_f32_e32 v95, 1.0, v89
	v_mul_f32_e32 v87, v93, v87
	v_exp_f32_e32 v89, v87
	v_rcp_f32_e32 v87, v95
	v_fmamk_f32 v95, v167, 0xbfb8aa3b, v170
	v_exp_f32_e32 v95, v95
	s_waitcnt lgkmcnt(0)
; template <bool PASS_C>
; DEVI void lru_item(const P& p, int item, int next_item, uint4& u0, uint4& u1, uint4& u2, float& cpre, char* smem) {
;     ...
;     float av[4][2][4], bv[4][2][4], apre[4][2], bpre[4][2];
; #pragma unroll
;     for (int nn = 0; nn < 4; ++nn) {
;         const int ch = 16 * nn + fr;
;         float uc[4];
; #pragma unroll
;         for (int j = 0; j < 4; ++j) {
;             const int tl = 16 * w + 4 * fq + j;
;             uc[j] = bf2f(*(const bf16_t*)(ucb + tl * 128 + ((((ch >> 3)) ^ (tl & 7)) << 4) + (ch & 7) * 2));
;         }
; #pragma unroll
;         for (int d = 0; d < 2; ++d) {
;             const float ba = prm[(5 + d) * 64 + ch], bx = prm[(7 + d) * 64 + ch], nsp8 = prm[(9 + d) * 64 + ch];
; #pragma unroll
;             for (int j = 0; j < 4; ++j) {
;                 const float r = __builtin_amdgcn_rcpf(1.0f + __builtin_amdgcn_exp2f(__builtin_fmaf(acc[(2 * d) * 4 + nn][j], -LOG2E, ba)));
;                 const float ig = __builtin_amdgcn_rcpf(1.0f + __builtin_amdgcn_exp2f(__builtin_fmaf(acc[(2 * d + 1) * 4 + nn][j], -LOG2E, bx)));
;                 const float a_ = __builtin_amdgcn_exp2f(nsp8 * r);
;                 av[nn][d][j] = a_;
;                 bv[nn][d][j] = __builtin_amdgcn_sqrtf(__builtin_fmaf(-a_, a_, 1.0f)) * ig * uc[j];
;             }
;             float A = 1.f, Bq = 0.f;
;             if (d == 0) {
; #pragma unroll
;                 for (int j = 0; j < 4; ++j) { Bq = av[nn][d][j] * Bq + bv[nn][d][j]; A *= av[nn][d][j]; }
;             } else {
; #pragma unroll
;                 for (int j = 3; j >= 0; --j) { Bq = av[nn][d][j] * Bq + bv[nn][d][j]; A *= av[nn][d][j]; }
;             }
;             float Ag[4], Bg[4];
;             rowgather4(A, Ag); rowgather4(Bq, Bg);
;             float AW = 1.f, BW = 0.f, AP = 1.f, BP = 0.f;
;             if (d == 0) {
; #pragma unroll
;                 for (int g = 0; g < 4; ++g) {
;                     if (g == fq) { AP = AW; BP = BW; }
;                     BW = Ag[g] * BW + Bg[g]; AW *= Ag[g];
;                 }
;             } else {
; #pragma unroll
;                 for (int g = 3; g >= 0; --g) {
;                     if (g == fq) { AP = AW; BP = BW; }
;                     BW = Ag[g] * BW + Bg[g]; AW *= Ag[g];
;                 }
;             }
;             apre[nn][d] = AP; bpre[nn][d] = BP;
	v_lshlrev_b32_e32 v163, 16, v91
	v_fma_f32 v97, -v89, v89, 1.0
	v_sqrt_f32_e32 v97, v97
	v_add_f32_e32 v91, 1.0, v95
	v_rcp_f32_e32 v91, v91
	v_fmamk_f32 v95, v185, 0xbfb8aa3b, v171
	v_exp_f32_e32 v95, v95
	v_mul_f32_e32 v87, v87, v97
	v_mul_f32_e32 v91, v93, v91
	v_exp_f32_e32 v91, v91
	v_add_f32_e32 v95, 1.0, v95
	v_rcp_f32_e32 v95, v95
	v_exp_f32_e32 v101, v101
	v_fma_f32 v97, -v91, v91, 1.0
	v_sqrt_f32_e32 v97, v97
	v_fmac_f32_e32 v171, 0xbfb8aa3b, v187
	v_exp_f32_e32 v105, v171
	v_mul_f32_e32 v87, v87, v164
	v_mul_f32_e32 v97, v95, v97
	v_add_f32_e32 v95, 1.0, v99
	v_add_f32_e32 v99, 1.0, v101
	v_fmamk_f32 v101, v169, 0xbfb8aa3b, v170
	v_exp_f32_e32 v101, v101
	v_rcp_f32_e32 v95, v95
	v_rcp_f32_e32 v99, v99
	v_add_f32_e32 v101, 1.0, v101
	v_rcp_f32_e32 v101, v101
	v_mul_f32_e32 v95, v93, v95
	v_exp_f32_e32 v95, v95
	v_mul_f32_e32 v93, v93, v101
	v_exp_f32_e32 v101, v93
	v_add_f32_e32 v93, 1.0, v105
	v_fma_f32 v103, -v95, v95, 1.0
	v_rcp_f32_e32 v105, v93
	v_fma_f32 v93, -v101, v101, 1.0
	v_sqrt_f32_e32 v103, v103
	v_sqrt_f32_e32 v157, v93
	v_mul_f32_e32 v93, v97, v161
	v_mul_f32_e32 v97, v99, v103
	v_mul_f32_e32 v99, v105, v157
	v_fma_f32 v105, 0, v89, v87
	v_mul_f32_e32 v97, v97, v162
	v_mul_f32_e32 v103, v89, v91
	v_fma_f32 v105, v91, v105, v93
	v_mul_f32_e32 v99, v99, v163
	v_mul_f32_e32 v103, v95, v103
	v_fma_f32 v105, v95, v105, v97
	v_mul_f32_e32 v103, v101, v103
	v_fma_f32 v105, v101, v105, v99
	v_mov_b32_e32 v159, v103
	v_mov_b32_e32 v157, v105
	s_nop 0
	v_permlane16_swap_b32_e32 v103, v159
	v_permlane16_swap_b32_e32 v105, v157
	v_mov_b32_e32 v160, v103
	v_mov_b32_e32 v158, v105
	s_nop 0
	v_permlane32_swap_b32_e32 v103, v160
	v_mov_b32_e32 v165, v159
	v_permlane32_swap_b32_e32 v105, v158
	v_mov_b32_e32 v166, v157
	v_permlane32_swap_b32_e32 v159, v165
	s_nop 0
	v_permlane32_swap_b32_e32 v157, v166
	v_fmac_f32_e32 v105, 0, v103
	v_fmac_f32_e32 v157, v105, v159
	v_mul_f32_e32 v159, v103, v159
	v_fmac_f32_e32 v158, v157, v160
	v_mul_f32_e32 v160, v159, v160
	s_and_saveexec_b64 s[28:29], s[10:11]
	v_mul_f32_e32 v167, v158, v165
	v_mul_f32_e32 v168, v160, v165
	v_add_f32_e32 v169, v167, v166
	ds_write_b64 v149, v[168:169] offset:52736
	s_or_b64 exec, exec, s[28:29]
	ds_read2st64_b32 v[166:167], v122 offset0:134 offset1:136
	ds_read_b32 v165, v122 offset:35328
	s_waitcnt lgkmcnt(1)
	v_fmamk_f32 v70, v70, 0xbfb8aa3b, v166
	v_exp_f32_e32 v70, v70
	v_fmamk_f32 v71, v71, 0xbfb8aa3b, v166
	v_exp_f32_e32 v71, v71
	v_fmamk_f32 v74, v74, 0xbfb8aa3b, v167
	v_add_f32_e32 v70, 1.0, v70
	v_rcp_f32_e32 v70, v70
	v_add_f32_e32 v71, 1.0, v71
	v_exp_f32_e32 v74, v74
	v_rcp_f32_e32 v71, v71
	s_waitcnt lgkmcnt(0)
	v_mul_f32_e32 v70, v165, v70
	v_exp_f32_e32 v70, v70
	v_fmamk_f32 v75, v75, 0xbfb8aa3b, v167
	v_add_f32_e32 v74, 1.0, v74
	v_mul_f32_e32 v71, v165, v71
	v_fma_f32 v168, -v70, v70, 1.0
	v_fmamk_f32 v72, v72, 0xbfb8aa3b, v166
	v_fmamk_f32 v73, v73, 0xbfb8aa3b, v166
	v_exp_f32_e32 v75, v75
	v_rcp_f32_e32 v74, v74
	v_exp_f32_e32 v71, v71
	v_sqrt_f32_e32 v168, v168
	v_exp_f32_e32 v72, v72
	v_exp_f32_e32 v73, v73
	v_add_f32_e32 v75, 1.0, v75
	v_fma_f32 v169, -v71, v71, 1.0
	v_mul_f32_e32 v74, v74, v168
	v_fmamk_f32 v76, v76, 0xbfb8aa3b, v167
	v_add_f32_e32 v72, 1.0, v72
	v_add_f32_e32 v73, 1.0, v73
	v_rcp_f32_e32 v75, v75
	v_mul_f32_e32 v74, v74, v164
	v_sqrt_f32_e32 v164, v169
	v_exp_f32_e32 v76, v76
	v_rcp_f32_e32 v72, v72
	v_rcp_f32_e32 v73, v73
	v_fmac_f32_e32 v167, 0xbfb8aa3b, v77
	v_mul_f32_e32 v164, v75, v164
	v_add_f32_e32 v75, 1.0, v76
	v_mul_f32_e32 v72, v165, v72
	v_exp_f32_e32 v77, v167
	v_mul_f32_e32 v73, v165, v73
	v_exp_f32_e32 v72, v72
	v_rcp_f32_e32 v76, v75
	v_exp_f32_e32 v75, v73
	v_add_f32_e32 v73, 1.0, v77
	v_fma_f32 v166, -v72, v72, 1.0
	v_rcp_f32_e32 v77, v73
	v_fma_f32 v73, -v75, v75, 1.0
	v_sqrt_f32_e32 v165, v166
	v_sqrt_f32_e32 v166, v73
	v_mul_f32_e32 v73, v164, v161
	v_mul_f32_e32 v161, v75, v72
	v_mul_f32_e32 v76, v76, v165
	v_mul_f32_e32 v77, v77, v166
	v_mul_f32_e32 v77, v77, v163
	v_mul_f32_e32 v161, v71, v161
	v_mul_f32_e32 v76, v76, v162
	v_mul_f32_e32 v165, v70, v161
	v_fma_f32 v161, 0, v75, v77
	v_fma_f32 v161, v72, v161, v76
	v_fma_f32 v161, v71, v161, v73
	v_fma_f32 v168, v70, v161, v74
	v_mov_b32_e32 v167, v165
	v_mov_b32_e32 v161, v168
	s_nop 0
	v_permlane16_swap_b32_e32 v165, v167
	v_permlane16_swap_b32_e32 v168, v161
	v_mov_b32_e32 v162, v167
	v_mov_b32_e32 v164, v161
	v_mov_b32_e32 v166, v165
	v_permlane32_swap_b32_e32 v167, v162
	v_mov_b32_e32 v163, v168
	v_permlane32_swap_b32_e32 v161, v164
	v_permlane32_swap_b32_e32 v165, v166
	v_permlane32_swap_b32_e32 v168, v163
	v_fmac_f32_e32 v164, 0, v162
	v_fmac_f32_e32 v163, v164, v166
	v_mul_f32_e32 v166, v166, v162
	v_fmac_f32_e32 v161, v163, v167
	v_mul_f32_e32 v167, v166, v167
	s_and_saveexec_b64 s[28:29], s[10:11]
	v_mul_f32_e32 v169, v161, v165
	v_mul_f32_e32 v170, v167, v165
	v_add_f32_e32 v171, v169, v168
	ds_write_b64 v149, v[170:171] offset:53248
	s_or_b64 exec, exec, s[28:29]
	v_add_u32_e32 v186, 64, v122
	ds_read2st64_b32 v[168:169], v186 offset0:133 offset1:135
	ds_read_u16 v165, v134 offset:44544
	ds_read_u16 v170, v135 offset:44544
	ds_read_u16 v171, v136 offset:44544
	ds_read_u16 v173, v137 offset:44544
	ds_read_b32 v187, v122 offset:35136
	s_waitcnt lgkmcnt(4)
	v_lshlrev_b32_e32 v185, 16, v165
	s_waitcnt lgkmcnt(3)
	v_lshlrev_b32_e32 v183, 16, v170
	s_waitcnt lgkmcnt(2)
	v_lshlrev_b32_e32 v177, 16, v171
	v_fmamk_f32 v62, v62, 0xbfb8aa3b, v168
	v_exp_f32_e32 v62, v62
	v_fmamk_f32 v63, v63, 0xbfb8aa3b, v168
	v_fmamk_f32 v66, v66, 0xbfb8aa3b, v169
	v_exp_f32_e32 v63, v63
	v_add_f32_e32 v62, 1.0, v62
	v_rcp_f32_e32 v62, v62
	v_exp_f32_e32 v66, v66
	v_add_f32_e32 v63, 1.0, v63
	v_rcp_f32_e32 v63, v63
	s_waitcnt lgkmcnt(0)
; template <bool PASS_C>
; DEVI void lru_item(const P& p, int item, int next_item, uint4& u0, uint4& u1, uint4& u2, float& cpre, char* smem) {
;     ...
;     float av[4][2][4], bv[4][2][4], apre[4][2], bpre[4][2];
; #pragma unroll
;     for (int nn = 0; nn < 4; ++nn) {
;         const int ch = 16 * nn + fr;
;         float uc[4];
; #pragma unroll
;         for (int j = 0; j < 4; ++j) {
;             const int tl = 16 * w + 4 * fq + j;
;             uc[j] = bf2f(*(const bf16_t*)(ucb + tl * 128 + ((((ch >> 3)) ^ (tl & 7)) << 4) + (ch & 7) * 2));
;         }
; #pragma unroll
;         for (int d = 0; d < 2; ++d) {
;             const float ba = prm[(5 + d) * 64 + ch], bx = prm[(7 + d) * 64 + ch], nsp8 = prm[(9 + d) * 64 + ch];
; #pragma unroll
;             for (int j = 0; j < 4; ++j) {
;                 const float r = __builtin_amdgcn_rcpf(1.0f + __builtin_amdgcn_exp2f(__builtin_fmaf(acc[(2 * d) * 4 + nn][j], -LOG2E, ba)));
;                 const float ig = __builtin_amdgcn_rcpf(1.0f + __builtin_amdgcn_exp2f(__builtin_fmaf(acc[(2 * d + 1) * 4 + nn][j], -LOG2E, bx)));
;                 const float a_ = __builtin_amdgcn_exp2f(nsp8 * r);
;                 av[nn][d][j] = a_;
;                 bv[nn][d][j] = __builtin_amdgcn_sqrtf(__builtin_fmaf(-a_, a_, 1.0f)) * ig * uc[j];
;             }
;             float A = 1.f, Bq = 0.f;
;             if (d == 0) {
; #pragma unroll
;                 for (int j = 0; j < 4; ++j) { Bq = av[nn][d][j] * Bq + bv[nn][d][j]; A *= av[nn][d][j]; }
;             } else {
; #pragma unroll
;                 for (int j = 3; j >= 0; --j) { Bq = av[nn][d][j] * Bq + bv[nn][d][j]; A *= av[nn][d][j]; }
;             }
;             float Ag[4], Bg[4];
;             rowgather4(A, Ag); rowgather4(Bq, Bg);
;             float AW = 1.f, BW = 0.f, AP = 1.f, BP = 0.f;
;             if (d == 0) {
; #pragma unroll
;                 for (int g = 0; g < 4; ++g) {
;                     if (g == fq) { AP = AW; BP = BW; }
;                     BW = Ag[g] * BW + Bg[g]; AW *= Ag[g];
;                 }
;             } else {
; #pragma unroll
;                 for (int g = 3; g >= 0; --g) {
;                     if (g == fq) { AP = AW; BP = BW; }
;                     BW = Ag[g] * BW + Bg[g]; AW *= Ag[g];
;                 }
;             }
;             apre[nn][d] = AP; bpre[nn][d] = BP;
	v_mul_f32_e32 v62, v187, v62
	v_add_f32_e32 v165, 1.0, v66
	v_exp_f32_e32 v66, v62
	v_rcp_f32_e32 v62, v165
	v_fmamk_f32 v67, v67, 0xbfb8aa3b, v169
	v_mul_f32_e32 v63, v187, v63
	v_fma_f32 v165, -v66, v66, 1.0
	v_sqrt_f32_e32 v165, v165
	v_exp_f32_e32 v67, v67
	v_exp_f32_e32 v63, v63
	v_fmamk_f32 v64, v64, 0xbfb8aa3b, v168
	v_exp_f32_e32 v64, v64
	v_mul_f32_e32 v62, v62, v165
	v_add_f32_e32 v67, 1.0, v67
	v_fma_f32 v165, -v63, v63, 1.0
	v_rcp_f32_e32 v67, v67
	v_sqrt_f32_e32 v165, v165
	v_add_f32_e32 v64, 1.0, v64
	v_rcp_f32_e32 v64, v64
	v_fmamk_f32 v65, v65, 0xbfb8aa3b, v168
	v_mul_f32_e32 v67, v67, v165
	v_exp_f32_e32 v165, v65
	v_mul_f32_e32 v64, v187, v64
	v_exp_f32_e32 v65, v64
	v_fmamk_f32 v68, v68, 0xbfb8aa3b, v169
	v_add_f32_e32 v64, 1.0, v165
	v_rcp_f32_e32 v64, v64
	v_fmac_f32_e32 v169, 0xbfb8aa3b, v69
	v_exp_f32_e32 v168, v169
	v_exp_f32_e32 v68, v68
	v_mul_f32_e32 v64, v187, v64
	v_exp_f32_e32 v69, v64
	v_add_f32_e32 v64, 1.0, v168
	v_add_f32_e32 v68, 1.0, v68
	v_fma_f32 v165, -v65, v65, 1.0
	v_rcp_f32_e32 v168, v64
	v_fma_f32 v64, -v69, v69, 1.0
	v_rcp_f32_e32 v68, v68
	v_sqrt_f32_e32 v165, v165
	v_sqrt_f32_e32 v169, v64
	v_mul_f32_e32 v62, v62, v185
	v_mul_f32_e32 v64, v67, v183
	v_mul_f32_e32 v67, v68, v165
	v_mul_f32_e32 v68, v168, v169
	v_fma_f32 v168, 0, v66, v62
	v_lshlrev_b32_e32 v184, 16, v173
	v_mul_f32_e32 v67, v67, v177
	v_mul_f32_e32 v165, v66, v63
	v_fma_f32 v168, v63, v168, v64
	v_mul_f32_e32 v68, v68, v184
	v_mul_f32_e32 v165, v65, v165
	v_fma_f32 v168, v65, v168, v67
	v_mul_f32_e32 v165, v69, v165
	v_fma_f32 v168, v69, v168, v68
	v_mov_b32_e32 v171, v165
	v_mov_b32_e32 v169, v168
	s_nop 0
	v_permlane16_swap_b32_e32 v165, v171
	v_permlane16_swap_b32_e32 v168, v169
	v_mov_b32_e32 v173, v165
	v_mov_b32_e32 v170, v168
	s_nop 0
	v_permlane32_swap_b32_e32 v165, v173
	v_mov_b32_e32 v187, v171
	v_permlane32_swap_b32_e32 v168, v170
	v_mov_b32_e32 v188, v169
	v_permlane32_swap_b32_e32 v171, v187
	s_nop 0
	v_permlane32_swap_b32_e32 v169, v188
	v_fmac_f32_e32 v168, 0, v165
	v_fmac_f32_e32 v169, v168, v171
	v_mul_f32_e32 v171, v165, v171
	v_fmac_f32_e32 v170, v169, v173
	v_mul_f32_e32 v173, v171, v173
	s_and_saveexec_b64 s[28:29], s[10:11]
	v_mul_f32_e32 v189, v170, v187
	v_mul_f32_e32 v190, v173, v187
	v_add_f32_e32 v191, v189, v188
	ds_write_b64 v150, v[190:191] offset:52736
	s_or_b64 exec, exec, s[28:29]
	ds_read2st64_b32 v[186:187], v186 offset0:134 offset1:136
	ds_read_b32 v188, v122 offset:35392
	s_waitcnt lgkmcnt(1)
	v_fmamk_f32 v54, v54, 0xbfb8aa3b, v186
	v_exp_f32_e32 v54, v54
	v_fmamk_f32 v55, v55, 0xbfb8aa3b, v186
	v_exp_f32_e32 v55, v55
	v_fmamk_f32 v58, v58, 0xbfb8aa3b, v187
	v_add_f32_e32 v54, 1.0, v54
	v_rcp_f32_e32 v54, v54
	v_add_f32_e32 v55, 1.0, v55
	v_exp_f32_e32 v58, v58
	v_rcp_f32_e32 v55, v55
	s_waitcnt lgkmcnt(0)
	v_mul_f32_e32 v54, v188, v54
	v_exp_f32_e32 v54, v54
	v_fmamk_f32 v56, v56, 0xbfb8aa3b, v186
	v_fmamk_f32 v59, v59, 0xbfb8aa3b, v187
	v_add_f32_e32 v58, 1.0, v58
	v_mul_f32_e32 v55, v188, v55
	v_fma_f32 v189, -v54, v54, 1.0
	v_exp_f32_e32 v56, v56
	v_fmamk_f32 v57, v57, 0xbfb8aa3b, v186
	v_exp_f32_e32 v59, v59
	v_rcp_f32_e32 v58, v58
	v_exp_f32_e32 v55, v55
	v_sqrt_f32_e32 v189, v189
	v_exp_f32_e32 v57, v57
	v_add_f32_e32 v56, 1.0, v56
	v_add_f32_e32 v59, 1.0, v59
	v_fma_f32 v190, -v55, v55, 1.0
	v_mul_f32_e32 v58, v58, v189
	v_fmamk_f32 v60, v60, 0xbfb8aa3b, v187
	v_rcp_f32_e32 v56, v56
	v_add_f32_e32 v57, 1.0, v57
	v_rcp_f32_e32 v59, v59
	v_mul_f32_e32 v58, v58, v185
	v_sqrt_f32_e32 v185, v190
	v_exp_f32_e32 v60, v60
	v_rcp_f32_e32 v57, v57
	v_mul_f32_e32 v56, v188, v56
	v_fmac_f32_e32 v187, 0xbfb8aa3b, v61
	v_mul_f32_e32 v185, v59, v185
	v_add_f32_e32 v59, 1.0, v60
	v_exp_f32_e32 v56, v56
	v_exp_f32_e32 v61, v187
	v_mul_f32_e32 v57, v188, v57
	v_rcp_f32_e32 v60, v59
	v_exp_f32_e32 v59, v57
	v_fma_f32 v186, -v56, v56, 1.0
	v_add_f32_e32 v57, 1.0, v61
	v_sqrt_f32_e32 v186, v186
	v_rcp_f32_e32 v61, v57
	v_fma_f32 v57, -v59, v59, 1.0
	v_sqrt_f32_e32 v187, v57
	v_mul_f32_e32 v60, v60, v186
	v_mul_f32_e32 v60, v60, v177
	v_mul_f32_e32 v177, v59, v56
	v_mul_f32_e32 v61, v61, v187
	v_mul_f32_e32 v61, v61, v184
	v_mul_f32_e32 v177, v55, v177
	v_mul_f32_e32 v186, v54, v177
	v_fma_f32 v177, 0, v59, v61
	v_mul_f32_e32 v57, v185, v183
	v_fma_f32 v177, v56, v177, v60
	v_fma_f32 v177, v55, v177, v57
	v_fma_f32 v189, v54, v177, v58
	v_mov_b32_e32 v188, v186
	v_mov_b32_e32 v177, v189
	s_nop 0
	v_permlane16_swap_b32_e32 v186, v188
	v_permlane16_swap_b32_e32 v189, v177
	v_mov_b32_e32 v183, v188
	v_mov_b32_e32 v185, v177
	v_mov_b32_e32 v187, v186
	v_permlane32_swap_b32_e32 v188, v183
	v_mov_b32_e32 v184, v189
	v_permlane32_swap_b32_e32 v177, v185
	v_permlane32_swap_b32_e32 v186, v187
	v_permlane32_swap_b32_e32 v189, v184
	v_fmac_f32_e32 v185, 0, v183
	v_fmac_f32_e32 v184, v185, v187
	v_mul_f32_e32 v187, v187, v183
	v_fmac_f32_e32 v177, v184, v188
	v_mul_f32_e32 v188, v187, v188
	s_and_saveexec_b64 s[28:29], s[10:11]
	v_mul_f32_e32 v191, v177, v186
	v_mul_f32_e32 v190, v188, v186
	v_add_f32_e32 v191, v191, v189
	ds_write_b64 v150, v[190:191] offset:53248
	s_or_b64 exec, exec, s[28:29]
	v_add_u32_e32 v198, 0x80, v122
	ds_read2st64_b32 v[190:191], v198 offset0:133 offset1:135
	ds_read_u16 v186, v138 offset:44544
	ds_read_u16 v189, v139 offset:44544
	ds_read_u16 v192, v140 offset:44544
	ds_read_u16 v193, v141 offset:44544
	ds_read_b32 v199, v122 offset:35200
	s_waitcnt lgkmcnt(4)
	v_lshlrev_b32_e32 v197, 16, v186
	s_waitcnt lgkmcnt(3)
	v_lshlrev_b32_e32 v195, 16, v189
	s_waitcnt lgkmcnt(2)
; template <bool PASS_C>
; DEVI void lru_item(const P& p, int item, int next_item, uint4& u0, uint4& u1, uint4& u2, float& cpre, char* smem) {
;     ...
;     float av[4][2][4], bv[4][2][4], apre[4][2], bpre[4][2];
; #pragma unroll
;     for (int nn = 0; nn < 4; ++nn) {
;         const int ch = 16 * nn + fr;
;         float uc[4];
; #pragma unroll
;         for (int j = 0; j < 4; ++j) {
;             const int tl = 16 * w + 4 * fq + j;
;             uc[j] = bf2f(*(const bf16_t*)(ucb + tl * 128 + ((((ch >> 3)) ^ (tl & 7)) << 4) + (ch & 7) * 2));
;         }
; #pragma unroll
;         for (int d = 0; d < 2; ++d) {
;             const float ba = prm[(5 + d) * 64 + ch], bx = prm[(7 + d) * 64 + ch], nsp8 = prm[(9 + d) * 64 + ch];
; #pragma unroll
;             for (int j = 0; j < 4; ++j) {
;                 const float r = __builtin_amdgcn_rcpf(1.0f + __builtin_amdgcn_exp2f(__builtin_fmaf(acc[(2 * d) * 4 + nn][j], -LOG2E, ba)));
;                 const float ig = __builtin_amdgcn_rcpf(1.0f + __builtin_amdgcn_exp2f(__builtin_fmaf(acc[(2 * d + 1) * 4 + nn][j], -LOG2E, bx)));
;                 const float a_ = __builtin_amdgcn_exp2f(nsp8 * r);
;                 av[nn][d][j] = a_;
;                 bv[nn][d][j] = __builtin_amdgcn_sqrtf(__builtin_fmaf(-a_, a_, 1.0f)) * ig * uc[j];
;             }
;             float A = 1.f, Bq = 0.f;
;             if (d == 0) {
; #pragma unroll
;                 for (int j = 0; j < 4; ++j) { Bq = av[nn][d][j] * Bq + bv[nn][d][j]; A *= av[nn][d][j]; }
;             } else {
; #pragma unroll
;                 for (int j = 3; j >= 0; --j) { Bq = av[nn][d][j] * Bq + bv[nn][d][j]; A *= av[nn][d][j]; }
;             }
;             float Ag[4], Bg[4];
;             rowgather4(A, Ag); rowgather4(Bq, Bg);
;             float AW = 1.f, BW = 0.f, AP = 1.f, BP = 0.f;
;             if (d == 0) {
; #pragma unroll
;                 for (int g = 0; g < 4; ++g) {
;                     if (g == fq) { AP = AW; BP = BW; }
;                     BW = Ag[g] * BW + Bg[g]; AW *= Ag[g];
;                 }
;             } else {
; #pragma unroll
;                 for (int g = 3; g >= 0; --g) {
;                     if (g == fq) { AP = AW; BP = BW; }
;                     BW = Ag[g] * BW + Bg[g]; AW *= Ag[g];
;                 }
;             }
;             apre[nn][d] = AP; bpre[nn][d] = BP;
	v_lshlrev_b32_e32 v194, 16, v192
	v_fmamk_f32 v46, v46, 0xbfb8aa3b, v190
	v_exp_f32_e32 v46, v46
	v_fmamk_f32 v47, v47, 0xbfb8aa3b, v190
	v_fmamk_f32 v50, v50, 0xbfb8aa3b, v191
	v_exp_f32_e32 v47, v47
	v_add_f32_e32 v46, 1.0, v46
	v_rcp_f32_e32 v46, v46
	v_exp_f32_e32 v50, v50
	v_add_f32_e32 v47, 1.0, v47
	v_rcp_f32_e32 v47, v47
	s_waitcnt lgkmcnt(0)
	v_mul_f32_e32 v46, v199, v46
	v_add_f32_e32 v186, 1.0, v50
	v_exp_f32_e32 v50, v46
	v_rcp_f32_e32 v46, v186
	v_fmamk_f32 v51, v51, 0xbfb8aa3b, v191
	v_mul_f32_e32 v47, v199, v47
	v_fma_f32 v186, -v50, v50, 1.0
	v_sqrt_f32_e32 v186, v186
	v_exp_f32_e32 v51, v51
	v_exp_f32_e32 v47, v47
	v_fmamk_f32 v48, v48, 0xbfb8aa3b, v190
	v_exp_f32_e32 v48, v48
	v_mul_f32_e32 v46, v46, v186
	v_add_f32_e32 v51, 1.0, v51
	v_fma_f32 v186, -v47, v47, 1.0
	v_rcp_f32_e32 v51, v51
	v_sqrt_f32_e32 v186, v186
	v_add_f32_e32 v48, 1.0, v48
	v_rcp_f32_e32 v48, v48
	v_fmamk_f32 v49, v49, 0xbfb8aa3b, v190
	v_mul_f32_e32 v51, v51, v186
	v_exp_f32_e32 v186, v49
	v_mul_f32_e32 v48, v199, v48
	v_exp_f32_e32 v49, v48
	v_fmamk_f32 v52, v52, 0xbfb8aa3b, v191
	v_add_f32_e32 v48, 1.0, v186
	v_rcp_f32_e32 v48, v48
	v_fmac_f32_e32 v191, 0xbfb8aa3b, v53
	v_exp_f32_e32 v189, v191
	v_exp_f32_e32 v52, v52
	v_mul_f32_e32 v48, v199, v48
	v_exp_f32_e32 v53, v48
	v_add_f32_e32 v48, 1.0, v189
	v_add_f32_e32 v52, 1.0, v52
	v_fma_f32 v186, -v49, v49, 1.0
	v_rcp_f32_e32 v189, v48
	v_fma_f32 v48, -v53, v53, 1.0
	v_rcp_f32_e32 v52, v52
	v_sqrt_f32_e32 v186, v186
	v_sqrt_f32_e32 v190, v48
	v_mul_f32_e32 v46, v46, v197
	v_mul_f32_e32 v48, v51, v195
	v_mul_f32_e32 v51, v52, v186
	v_mul_f32_e32 v52, v189, v190
	v_fma_f32 v189, 0, v50, v46
	v_lshlrev_b32_e32 v196, 16, v193
	v_mul_f32_e32 v51, v51, v194
	v_mul_f32_e32 v186, v50, v47
	v_fma_f32 v189, v47, v189, v48
	v_mul_f32_e32 v52, v52, v196
	v_mul_f32_e32 v186, v49, v186
	v_fma_f32 v189, v49, v189, v51
	v_mul_f32_e32 v186, v53, v186
	v_fma_f32 v189, v53, v189, v52
	v_mov_b32_e32 v192, v186
	v_mov_b32_e32 v190, v189
	s_nop 0
	v_permlane16_swap_b32_e32 v186, v192
	v_permlane16_swap_b32_e32 v189, v190
	v_mov_b32_e32 v193, v186
	v_mov_b32_e32 v191, v189
	s_nop 0
	v_permlane32_swap_b32_e32 v186, v193
	v_mov_b32_e32 v199, v192
	v_permlane32_swap_b32_e32 v189, v191
	v_mov_b32_e32 v200, v190
	v_permlane32_swap_b32_e32 v192, v199
	s_nop 0
	v_permlane32_swap_b32_e32 v190, v200
	v_fmac_f32_e32 v189, 0, v186
	v_fmac_f32_e32 v190, v189, v192
	v_mul_f32_e32 v192, v186, v192
	v_fmac_f32_e32 v191, v190, v193
	v_mul_f32_e32 v193, v192, v193
	s_and_saveexec_b64 s[28:29], s[10:11]
	v_mul_f32_e32 v201, v191, v199
	v_mul_f32_e32 v202, v193, v199
	v_add_f32_e32 v203, v201, v200
	ds_write_b64 v151, v[202:203] offset:52736
	s_or_b64 exec, exec, s[28:29]
	ds_read2st64_b32 v[198:199], v198 offset0:134 offset1:136
	ds_read_b32 v200, v122 offset:35456
	s_waitcnt lgkmcnt(1)
	v_fmamk_f32 v38, v38, 0xbfb8aa3b, v198
	v_exp_f32_e32 v38, v38
	v_fmamk_f32 v39, v39, 0xbfb8aa3b, v198
	v_exp_f32_e32 v39, v39
	v_fmamk_f32 v42, v42, 0xbfb8aa3b, v199
	v_add_f32_e32 v38, 1.0, v38
	v_rcp_f32_e32 v38, v38
	v_add_f32_e32 v39, 1.0, v39
	v_exp_f32_e32 v42, v42
	v_rcp_f32_e32 v39, v39
	s_waitcnt lgkmcnt(0)
	v_mul_f32_e32 v38, v200, v38
	v_exp_f32_e32 v38, v38
	v_fmamk_f32 v40, v40, 0xbfb8aa3b, v198
	v_fmamk_f32 v43, v43, 0xbfb8aa3b, v199
	v_add_f32_e32 v42, 1.0, v42
	v_mul_f32_e32 v39, v200, v39
	v_fma_f32 v201, -v38, v38, 1.0
	v_exp_f32_e32 v40, v40
	v_fmamk_f32 v41, v41, 0xbfb8aa3b, v198
	v_exp_f32_e32 v43, v43
	v_rcp_f32_e32 v42, v42
	v_exp_f32_e32 v39, v39
	v_sqrt_f32_e32 v201, v201
	v_exp_f32_e32 v41, v41
	v_add_f32_e32 v40, 1.0, v40
	v_add_f32_e32 v43, 1.0, v43
	v_fma_f32 v202, -v39, v39, 1.0
	v_mul_f32_e32 v42, v42, v201
	v_fmamk_f32 v44, v44, 0xbfb8aa3b, v199
	v_rcp_f32_e32 v40, v40
	v_add_f32_e32 v41, 1.0, v41
	v_rcp_f32_e32 v43, v43
	v_mul_f32_e32 v42, v42, v197
	v_sqrt_f32_e32 v197, v202
	v_exp_f32_e32 v44, v44
	v_rcp_f32_e32 v41, v41
	v_mul_f32_e32 v40, v200, v40
	v_fmac_f32_e32 v199, 0xbfb8aa3b, v45
	v_mul_f32_e32 v197, v43, v197
	v_add_f32_e32 v43, 1.0, v44
	v_exp_f32_e32 v40, v40
	v_exp_f32_e32 v45, v199
	v_mul_f32_e32 v41, v200, v41
	v_rcp_f32_e32 v44, v43
	v_exp_f32_e32 v43, v41
	v_fma_f32 v198, -v40, v40, 1.0
	v_add_f32_e32 v41, 1.0, v45
	v_sqrt_f32_e32 v198, v198
	v_rcp_f32_e32 v45, v41
	v_fma_f32 v41, -v43, v43, 1.0
	v_sqrt_f32_e32 v199, v41
	v_mul_f32_e32 v44, v44, v198
	v_mul_f32_e32 v44, v44, v194
	v_mul_f32_e32 v194, v43, v40
	v_mul_f32_e32 v45, v45, v199
	v_mul_f32_e32 v45, v45, v196
	v_mul_f32_e32 v194, v39, v194
	v_mul_f32_e32 v198, v38, v194
	v_fma_f32 v194, 0, v43, v45
	v_mul_f32_e32 v41, v197, v195
	v_fma_f32 v194, v40, v194, v44
	v_fma_f32 v194, v39, v194, v41
	v_fma_f32 v200, v38, v194, v42
	v_mov_b32_e32 v201, v198
	v_mov_b32_e32 v194, v200
	s_nop 0
	v_permlane16_swap_b32_e32 v198, v201
	v_permlane16_swap_b32_e32 v200, v194
	v_mov_b32_e32 v195, v201
	v_mov_b32_e32 v197, v194
	v_mov_b32_e32 v199, v198
	v_permlane32_swap_b32_e32 v201, v195
	v_mov_b32_e32 v196, v200
	v_permlane32_swap_b32_e32 v194, v197
	v_permlane32_swap_b32_e32 v198, v199
	v_permlane32_swap_b32_e32 v200, v196
	v_fmac_f32_e32 v197, 0, v195
	v_fmac_f32_e32 v196, v197, v199
	v_mul_f32_e32 v199, v199, v195
	v_fmac_f32_e32 v194, v196, v201
	v_mul_f32_e32 v201, v199, v201
	s_and_saveexec_b64 s[28:29], s[10:11]
	v_mul_f32_e32 v203, v194, v198
	v_mul_f32_e32 v202, v201, v198
	v_add_f32_e32 v203, v203, v200
	ds_write_b64 v151, v[202:203] offset:53248
	s_or_b64 exec, exec, s[28:29]
	v_add_u32_e32 v210, 0xc0, v122
	ds_read2st64_b32 v[202:203], v210 offset0:133 offset1:135
	ds_read_u16 v198, v142 offset:44544
	ds_read_u16 v200, v143 offset:44544
	ds_read_u16 v204, v144 offset:44544
	ds_read_u16 v205, v145 offset:44544
	ds_read_b32 v211, v122 offset:35264
	s_waitcnt lgkmcnt(4)
; template <bool PASS_C>
; DEVI void lru_item(const P& p, int item, int next_item, uint4& u0, uint4& u1, uint4& u2, float& cpre, char* smem) {
;     ...
;     float av[4][2][4], bv[4][2][4], apre[4][2], bpre[4][2];
; #pragma unroll
;     for (int nn = 0; nn < 4; ++nn) {
;         const int ch = 16 * nn + fr;
;         float uc[4];
; #pragma unroll
;         for (int j = 0; j < 4; ++j) {
;             const int tl = 16 * w + 4 * fq + j;
;             uc[j] = bf2f(*(const bf16_t*)(ucb + tl * 128 + ((((ch >> 3)) ^ (tl & 7)) << 4) + (ch & 7) * 2));
;         }
; #pragma unroll
;         for (int d = 0; d < 2; ++d) {
;             const float ba = prm[(5 + d) * 64 + ch], bx = prm[(7 + d) * 64 + ch], nsp8 = prm[(9 + d) * 64 + ch];
; #pragma unroll
;             for (int j = 0; j < 4; ++j) {
;                 const float r = __builtin_amdgcn_rcpf(1.0f + __builtin_amdgcn_exp2f(__builtin_fmaf(acc[(2 * d) * 4 + nn][j], -LOG2E, ba)));
;                 const float ig = __builtin_amdgcn_rcpf(1.0f + __builtin_amdgcn_exp2f(__builtin_fmaf(acc[(2 * d + 1) * 4 + nn][j], -LOG2E, bx)));
;                 const float a_ = __builtin_amdgcn_exp2f(nsp8 * r);
;                 av[nn][d][j] = a_;
;                 bv[nn][d][j] = __builtin_amdgcn_sqrtf(__builtin_fmaf(-a_, a_, 1.0f)) * ig * uc[j];
;             }
;             float A = 1.f, Bq = 0.f;
;             if (d == 0) {
; #pragma unroll
;                 for (int j = 0; j < 4; ++j) { Bq = av[nn][d][j] * Bq + bv[nn][d][j]; A *= av[nn][d][j]; }
;             } else {
; #pragma unroll
;                 for (int j = 3; j >= 0; --j) { Bq = av[nn][d][j] * Bq + bv[nn][d][j]; A *= av[nn][d][j]; }
;             }
;             float Ag[4], Bg[4];
;             rowgather4(A, Ag); rowgather4(Bq, Bg);
;             float AW = 1.f, BW = 0.f, AP = 1.f, BP = 0.f;
;             if (d == 0) {
; #pragma unroll
;                 for (int g = 0; g < 4; ++g) {
;                     if (g == fq) { AP = AW; BP = BW; }
;                     BW = Ag[g] * BW + Bg[g]; AW *= Ag[g];
;                 }
;             } else {
; #pragma unroll
;                 for (int g = 3; g >= 0; --g) {
;                     if (g == fq) { AP = AW; BP = BW; }
;                     BW = Ag[g] * BW + Bg[g]; AW *= Ag[g];
;                 }
;             }
;             apre[nn][d] = AP; bpre[nn][d] = BP;
	v_lshlrev_b32_e32 v209, 16, v198
	s_waitcnt lgkmcnt(3)
	v_lshlrev_b32_e32 v207, 16, v200
	s_waitcnt lgkmcnt(2)
	v_lshlrev_b32_e32 v206, 16, v204
	v_fmamk_f32 v30, v30, 0xbfb8aa3b, v202
	v_exp_f32_e32 v30, v30
	v_fmamk_f32 v31, v31, 0xbfb8aa3b, v202
	v_fmamk_f32 v34, v34, 0xbfb8aa3b, v203
	v_exp_f32_e32 v31, v31
	v_add_f32_e32 v30, 1.0, v30
	v_rcp_f32_e32 v30, v30
	v_exp_f32_e32 v34, v34
	v_add_f32_e32 v31, 1.0, v31
	v_rcp_f32_e32 v31, v31
	s_waitcnt lgkmcnt(0)
	v_mul_f32_e32 v30, v211, v30
	v_add_f32_e32 v198, 1.0, v34
	v_exp_f32_e32 v34, v30
	v_rcp_f32_e32 v30, v198
	v_fmamk_f32 v35, v35, 0xbfb8aa3b, v203
	v_mul_f32_e32 v31, v211, v31
	v_fma_f32 v198, -v34, v34, 1.0
	v_sqrt_f32_e32 v198, v198
	v_exp_f32_e32 v35, v35
	v_exp_f32_e32 v31, v31
	v_fmamk_f32 v32, v32, 0xbfb8aa3b, v202
	v_exp_f32_e32 v32, v32
	v_mul_f32_e32 v30, v30, v198
	v_add_f32_e32 v35, 1.0, v35
	v_fma_f32 v198, -v31, v31, 1.0
	v_rcp_f32_e32 v35, v35
	v_sqrt_f32_e32 v198, v198
	v_add_f32_e32 v32, 1.0, v32
	v_rcp_f32_e32 v32, v32
	v_fmamk_f32 v33, v33, 0xbfb8aa3b, v202
	v_mul_f32_e32 v35, v35, v198
	v_exp_f32_e32 v198, v33
	v_mul_f32_e32 v32, v211, v32
	v_exp_f32_e32 v33, v32
	v_fmamk_f32 v36, v36, 0xbfb8aa3b, v203
	v_add_f32_e32 v32, 1.0, v198
	v_rcp_f32_e32 v32, v32
	v_fmac_f32_e32 v203, 0xbfb8aa3b, v37
	v_exp_f32_e32 v200, v203
	v_exp_f32_e32 v36, v36
	v_mul_f32_e32 v32, v211, v32
	v_exp_f32_e32 v37, v32
	v_add_f32_e32 v32, 1.0, v200
	v_add_f32_e32 v36, 1.0, v36
	v_fma_f32 v198, -v33, v33, 1.0
	v_rcp_f32_e32 v200, v32
	v_fma_f32 v32, -v37, v37, 1.0
	v_rcp_f32_e32 v36, v36
	v_sqrt_f32_e32 v198, v198
	v_sqrt_f32_e32 v202, v32
	v_mul_f32_e32 v30, v30, v209
	v_mul_f32_e32 v32, v35, v207
	v_mul_f32_e32 v35, v36, v198
	v_mul_f32_e32 v36, v200, v202
	v_fma_f32 v200, 0, v34, v30
	v_lshlrev_b32_e32 v208, 16, v205
	v_mul_f32_e32 v35, v35, v206
	v_mul_f32_e32 v198, v34, v31
	v_fma_f32 v200, v31, v200, v32
	v_mul_f32_e32 v36, v36, v208
	v_mul_f32_e32 v198, v33, v198
	v_fma_f32 v200, v33, v200, v35
	v_mul_f32_e32 v198, v37, v198
	v_fma_f32 v200, v37, v200, v36
	v_mov_b32_e32 v204, v198
	v_mov_b32_e32 v202, v200
	s_nop 0
	v_permlane16_swap_b32_e32 v198, v204
	v_permlane16_swap_b32_e32 v200, v202
	v_mov_b32_e32 v205, v198
	v_mov_b32_e32 v203, v200
	s_nop 0
	v_permlane32_swap_b32_e32 v198, v205
	v_mov_b32_e32 v211, v204
	v_permlane32_swap_b32_e32 v200, v203
	v_mov_b32_e32 v212, v202
	v_permlane32_swap_b32_e32 v204, v211
	s_nop 0
	v_permlane32_swap_b32_e32 v202, v212
	v_fmac_f32_e32 v200, 0, v198
	v_fmac_f32_e32 v202, v200, v204
	v_mul_f32_e32 v204, v198, v204
	v_fmac_f32_e32 v203, v202, v205
	v_mul_f32_e32 v205, v204, v205
	s_and_saveexec_b64 s[28:29], s[10:11]
	v_mul_f32_e32 v213, v203, v211
	v_mul_f32_e32 v214, v205, v211
	v_add_f32_e32 v215, v213, v212
	ds_write_b64 v152, v[214:215] offset:52736
	s_or_b64 exec, exec, s[28:29]
	ds_read2st64_b32 v[210:211], v210 offset0:134 offset1:136
	ds_read_b32 v212, v122 offset:35520
	s_waitcnt lgkmcnt(1)
	v_fmamk_f32 v22, v22, 0xbfb8aa3b, v210
	v_exp_f32_e32 v22, v22
	v_fmamk_f32 v23, v23, 0xbfb8aa3b, v210
	v_exp_f32_e32 v23, v23
	v_fmamk_f32 v26, v26, 0xbfb8aa3b, v211
	v_add_f32_e32 v22, 1.0, v22
	v_rcp_f32_e32 v22, v22
	v_add_f32_e32 v23, 1.0, v23
	v_exp_f32_e32 v26, v26
	v_rcp_f32_e32 v23, v23
	s_waitcnt lgkmcnt(0)
	v_mul_f32_e32 v22, v212, v22
	v_exp_f32_e32 v22, v22
	v_fmamk_f32 v24, v24, 0xbfb8aa3b, v210
	v_fmamk_f32 v27, v27, 0xbfb8aa3b, v211
	v_add_f32_e32 v26, 1.0, v26
	v_mul_f32_e32 v23, v212, v23
	v_fma_f32 v213, -v22, v22, 1.0
	v_exp_f32_e32 v24, v24
	v_fmamk_f32 v25, v25, 0xbfb8aa3b, v210
	v_exp_f32_e32 v27, v27
	v_rcp_f32_e32 v26, v26
	v_exp_f32_e32 v23, v23
	v_sqrt_f32_e32 v213, v213
	v_exp_f32_e32 v25, v25
	v_add_f32_e32 v24, 1.0, v24
	v_add_f32_e32 v27, 1.0, v27
	v_fma_f32 v214, -v23, v23, 1.0
	v_mul_f32_e32 v26, v26, v213
	v_fmamk_f32 v28, v28, 0xbfb8aa3b, v211
	v_rcp_f32_e32 v24, v24
	v_add_f32_e32 v25, 1.0, v25
	v_rcp_f32_e32 v27, v27
	v_mul_f32_e32 v26, v26, v209
	v_sqrt_f32_e32 v209, v214
	v_exp_f32_e32 v28, v28
	v_rcp_f32_e32 v25, v25
	v_mul_f32_e32 v24, v212, v24
	v_fmac_f32_e32 v211, 0xbfb8aa3b, v29
	v_mul_f32_e32 v209, v27, v209
	v_add_f32_e32 v27, 1.0, v28
	v_exp_f32_e32 v24, v24
	v_exp_f32_e32 v29, v211
	v_mul_f32_e32 v25, v212, v25
	v_rcp_f32_e32 v28, v27
	v_exp_f32_e32 v27, v25
	v_fma_f32 v210, -v24, v24, 1.0
	v_add_f32_e32 v25, 1.0, v29
	v_sqrt_f32_e32 v210, v210
	v_rcp_f32_e32 v29, v25
	v_fma_f32 v25, -v27, v27, 1.0
	v_sqrt_f32_e32 v211, v25
	v_mul_f32_e32 v28, v28, v210
	v_mul_f32_e32 v28, v28, v206
	v_mul_f32_e32 v206, v27, v24
	v_mul_f32_e32 v29, v29, v211
	v_mul_f32_e32 v29, v29, v208
	v_mul_f32_e32 v206, v23, v206
	v_mul_f32_e32 v212, v22, v206
	v_fma_f32 v206, 0, v27, v29
	v_mul_f32_e32 v25, v209, v207
	v_fma_f32 v206, v24, v206, v28
	v_fma_f32 v206, v23, v206, v25
	v_fma_f32 v213, v22, v206, v26
	v_mov_b32_e32 v211, v212
	v_mov_b32_e32 v207, v213
	s_nop 0
	v_permlane16_swap_b32_e32 v212, v211
	v_permlane16_swap_b32_e32 v213, v207
	v_mov_b32_e32 v206, v211
	v_mov_b32_e32 v209, v207
	v_mov_b32_e32 v210, v212
	v_permlane32_swap_b32_e32 v211, v206
	v_mov_b32_e32 v208, v213
	v_permlane32_swap_b32_e32 v207, v209
	v_permlane32_swap_b32_e32 v212, v210
	v_permlane32_swap_b32_e32 v213, v208
	v_fmac_f32_e32 v209, 0, v206
	v_fmac_f32_e32 v208, v209, v210
	v_mul_f32_e32 v210, v210, v206
	v_fmac_f32_e32 v207, v208, v211
	v_mul_f32_e32 v211, v210, v211
	s_and_saveexec_b64 s[28:29], s[10:11]
	v_mul_f32_e32 v214, v207, v212
	v_mul_f32_e32 v212, v211, v212
	v_add_f32_e32 v213, v214, v213
	ds_write_b64 v152, v[212:213] offset:53248
	s_or_b64 exec, exec, s[28:29]
	s_waitcnt lgkmcnt(0)
	s_barrier
; template <bool PASS_C>
; DEVI void lru_item(const P& p, int item, int next_item, uint4& u0, uint4& u1, uint4& u2, float& cpre, char* smem) {
;     ...
; #pragma unroll
;         for (int nn = 0; nn < 4; ++nn) {
;             const int ch = 16 * nn + fr;
;             float y[4];
;             {
;                 float hw = carry[ch];
; #pragma unroll
;                 for (int ww = 0; ww < 4; ++ww)
;                     if (ww < w) hw = wagg[((ww * 2 + 0) * 64 + ch) * 2] * hw + wagg[((ww * 2 + 0) * 64 + ch) * 2 + 1];
;                 float hh = apre[nn][0] * hw + bpre[nn][0];
; #pragma unroll
;                 for (int j = 0; j < 4; ++j) { hh = av[nn][0][j] * hh + bv[nn][0][j]; y[j] = hh; }
;             }
;             {
;                 float hw = carry[64 + ch];
; #pragma unroll
;     ...
;                     if (ww > w) hw = wagg[((ww * 2 + 1) * 64 + ch) * 2] * hw + wagg[((ww * 2 + 1) * 64 + ch) * 2 + 1];
;                 float hh = apre[nn][1] * hw + bpre[nn][1];
; #pragma unroll
;                 for (int j = 3; j >= 0; --j) { hh = av[nn][1][j] * hh + bv[nn][1][j]; y[j] += hh; }
;             }
; #pragma unroll
;             for (int j = 0; j < 4; ++j) ytile[(16 * w + 4 * fq + j) * 66 + ch] = y[j];
;         }
	ds_read_b32 v244, v122 offset:56832
	ds_read_b32 v245, v122 offset:57088
	ds_read_b64 v[232:233], v123 offset:52736
	ds_read_b64 v[234:235], v123 offset:53760
	ds_read_b64 v[236:237], v123 offset:54784
	ds_read_b64 v[238:239], v123 offset:56320
	ds_read_b64 v[240:241], v123 offset:55296
	ds_read_b64 v[242:243], v123 offset:54272
	ds_read_b32 v246, v122 offset:56896
	ds_read_b32 v247, v122 offset:57152
	ds_read_b64 v[218:219], v154 offset:52736
	ds_read_b64 v[220:221], v154 offset:53760
	ds_read_b64 v[222:223], v154 offset:54784
	ds_read_b64 v[224:225], v154 offset:56320
	ds_read_b64 v[226:227], v154 offset:55296
	ds_read_b64 v[228:229], v154 offset:54272
	s_waitcnt lgkmcnt(8)
	v_fma_f32 v248, v232, v244, v233
	v_cndmask_b32_e64 v212, v244, v248, s[4:5]
	v_fma_f32 v248, v234, v212, v235
	v_cndmask_b32_e64 v212, v212, v248, s[18:19]
	v_fma_f32 v248, v236, v212, v237
	v_cndmask_b32_e64 v212, v212, v248, s[20:21]
	v_fma_f32 v248, v238, v245, v239
	v_cndmask_b32_e64 v213, v245, v248, s[24:25]
	v_fma_f32 v248, v240, v213, v241
	v_cndmask_b32_e64 v213, v213, v248, s[8:9]
	v_fma_f32 v248, v242, v213, v243
	v_cndmask_b32_e64 v213, v213, v248, s[2:3]
	v_cndmask_b32_e64 v103, 1.0, v103, s[12:13]
	v_cndmask_b32_e64 v105, 0, v105, s[12:13]
	v_cndmask_b32_e64 v103, v103, v159, s[14:15]
	v_cndmask_b32_e64 v105, v105, v157, s[14:15]
	v_cndmask_b32_e64 v103, v103, v160, s[16:17]
	v_cndmask_b32_e64 v105, v105, v158, s[16:17]
	v_fmac_f32_e32 v105, v103, v212
	v_fmac_f32_e32 v87, v89, v105
	v_fmac_f32_e32 v93, v91, v87
	v_cndmask_b32_e64 v89, 1.0, v162, s[14:15]
	v_cndmask_b32_e64 v91, 0, v164, s[14:15]
	v_cndmask_b32_e64 v89, v89, v166, s[12:13]
	v_cndmask_b32_e64 v91, v91, v163, s[12:13]
	v_cndmask_b32_e64 v89, v89, v167, s[10:11]
	v_cndmask_b32_e64 v91, v91, v161, s[10:11]
	v_fmac_f32_e32 v91, v89, v213
	v_fmac_f32_e32 v77, v75, v91
	v_fmac_f32_e32 v76, v72, v77
	v_fmac_f32_e32 v73, v71, v76
	v_fmac_f32_e32 v97, v95, v93
	v_fmac_f32_e32 v74, v70, v73
	v_fmac_f32_e32 v99, v101, v97
	v_add_f32_e32 v71, v93, v73
	v_add_f32_e32 v73, v87, v74
	v_add_u32_e32 v70, 0x8c00, v153
	v_add_f32_e32 v75, v99, v77
	v_add_f32_e32 v72, v97, v76
	ds_write2_b32 v70, v73, v71 offset1:66
	ds_write2_b32 v70, v72, v75 offset0:132 offset1:198
	ds_read_b32 v244, v122 offset:56960
	ds_read_b32 v245, v122 offset:57216
	ds_read_b64 v[232:233], v155 offset:52736
	ds_read_b64 v[234:235], v155 offset:53760
	ds_read_b64 v[236:237], v155 offset:54784
	ds_read_b64 v[238:239], v155 offset:56320
	ds_read_b64 v[240:241], v155 offset:55296
	ds_read_b64 v[242:243], v155 offset:54272
	s_waitcnt lgkmcnt(10)
	v_fma_f32 v248, v218, v246, v219
	v_cndmask_b32_e64 v71, v246, v248, s[4:5]
	v_fma_f32 v248, v220, v71, v221
	v_cndmask_b32_e64 v71, v71, v248, s[18:19]
	v_fma_f32 v248, v222, v71, v223
	v_cndmask_b32_e64 v71, v71, v248, s[20:21]
	v_fma_f32 v248, v224, v247, v225
	v_cndmask_b32_e64 v72, v247, v248, s[24:25]
	v_fma_f32 v248, v226, v72, v227
	v_cndmask_b32_e64 v72, v72, v248, s[8:9]
	v_fma_f32 v248, v228, v72, v229
	v_cndmask_b32_e64 v72, v72, v248, s[2:3]
	v_cndmask_b32_e64 v73, 1.0, v165, s[12:13]
	v_cndmask_b32_e64 v74, 0, v168, s[12:13]
	v_cndmask_b32_e64 v73, v73, v171, s[14:15]
	v_cndmask_b32_e64 v74, v74, v169, s[14:15]
	v_cndmask_b32_e64 v73, v73, v173, s[16:17]
	v_cndmask_b32_e64 v74, v74, v170, s[16:17]
	v_fmac_f32_e32 v74, v73, v71
	v_fmac_f32_e32 v62, v66, v74
	v_fmac_f32_e32 v64, v63, v62
	v_fmac_f32_e32 v67, v65, v64
	v_cndmask_b32_e64 v63, 1.0, v183, s[14:15]
	v_cndmask_b32_e64 v65, 0, v185, s[14:15]
	v_cndmask_b32_e64 v63, v63, v187, s[12:13]
	v_cndmask_b32_e64 v65, v65, v184, s[12:13]
	v_cndmask_b32_e64 v63, v63, v188, s[10:11]
	v_cndmask_b32_e64 v65, v65, v177, s[10:11]
	v_fmac_f32_e32 v65, v63, v72
	v_fmac_f32_e32 v61, v59, v65
	v_fmac_f32_e32 v60, v56, v61
	v_fmac_f32_e32 v57, v55, v60
	v_fmac_f32_e32 v58, v54, v57
	v_fmac_f32_e32 v68, v69, v67
	v_add_f32_e32 v55, v64, v57
	v_add_f32_e32 v54, v62, v58
	v_add_f32_e32 v59, v68, v61
	v_add_f32_e32 v56, v67, v60
	ds_write2_b32 v70, v54, v55 offset0:16 offset1:82
	ds_write2_b32 v70, v56, v59 offset0:148 offset1:214
	ds_read_b32 v246, v122 offset:57024
	ds_read_b32 v247, v122 offset:57280
	ds_read_b64 v[218:219], v156 offset:52736
	ds_read_b64 v[220:221], v156 offset:53760
	ds_read_b64 v[222:223], v156 offset:54784
	ds_read_b64 v[224:225], v156 offset:56320
	ds_read_b64 v[226:227], v156 offset:55296
	ds_read_b64 v[228:229], v156 offset:54272
	s_waitcnt lgkmcnt(10)
	v_fma_f32 v248, v232, v244, v233
	v_cndmask_b32_e64 v54, v244, v248, s[4:5]
	v_fma_f32 v248, v234, v54, v235
	v_cndmask_b32_e64 v54, v54, v248, s[18:19]
	v_fma_f32 v248, v236, v54, v237
	v_cndmask_b32_e64 v54, v54, v248, s[20:21]
	v_fma_f32 v248, v238, v245, v239
	v_cndmask_b32_e64 v55, v245, v248, s[24:25]
	v_fma_f32 v248, v240, v55, v241
	v_cndmask_b32_e64 v55, v55, v248, s[8:9]
	v_fma_f32 v248, v242, v55, v243
	v_cndmask_b32_e64 v55, v55, v248, s[2:3]
	v_cndmask_b32_e64 v56, 1.0, v186, s[12:13]
	v_cndmask_b32_e64 v57, 0, v189, s[12:13]
	v_cndmask_b32_e64 v56, v56, v192, s[14:15]
	v_cndmask_b32_e64 v57, v57, v190, s[14:15]
	v_cndmask_b32_e64 v56, v56, v193, s[16:17]
	v_cndmask_b32_e64 v57, v57, v191, s[16:17]
	v_fmac_f32_e32 v57, v56, v54
	v_fmac_f32_e32 v46, v50, v57
	v_fmac_f32_e32 v48, v47, v46
	v_fmac_f32_e32 v51, v49, v48
	v_cndmask_b32_e64 v47, 1.0, v195, s[14:15]
	v_cndmask_b32_e64 v49, 0, v197, s[14:15]
	v_cndmask_b32_e64 v47, v47, v199, s[12:13]
	v_cndmask_b32_e64 v49, v49, v196, s[12:13]
	v_cndmask_b32_e64 v47, v47, v201, s[10:11]
	v_cndmask_b32_e64 v49, v49, v194, s[10:11]
	v_fmac_f32_e32 v49, v47, v55
	v_fmac_f32_e32 v45, v43, v49
	v_fmac_f32_e32 v44, v40, v45
	v_fmac_f32_e32 v41, v39, v44
	v_fmac_f32_e32 v42, v38, v41
	v_fmac_f32_e32 v52, v53, v51
	v_add_f32_e32 v39, v48, v41
	v_add_f32_e32 v38, v46, v42
	v_add_f32_e32 v43, v52, v45
	v_add_f32_e32 v40, v51, v44
	ds_write2_b32 v70, v38, v39 offset0:32 offset1:98
	ds_write2_b32 v70, v40, v43 offset0:164 offset1:230
	s_waitcnt lgkmcnt(2)
	v_fma_f32 v248, v218, v246, v219
	v_cndmask_b32_e64 v38, v246, v248, s[4:5]
	v_fma_f32 v248, v220, v38, v221
	v_cndmask_b32_e64 v38, v38, v248, s[18:19]
	v_fma_f32 v248, v222, v38, v223
	v_cndmask_b32_e64 v38, v38, v248, s[20:21]
	v_fma_f32 v248, v224, v247, v225
	v_cndmask_b32_e64 v39, v247, v248, s[24:25]
	v_fma_f32 v248, v226, v39, v227
	v_cndmask_b32_e64 v39, v39, v248, s[8:9]
	v_fma_f32 v248, v228, v39, v229
	v_cndmask_b32_e64 v39, v39, v248, s[2:3]
	s_branch .LBB0_720
